# duplicate lgkmcnt(0) waits after the asm-block waits removed in the GEMM main loops
# speedup vs baseline: 1.0530x; 1.0024x over previous
.LBB0_204:
	s_add_i32 s28, s8, 2
	s_add_u32 s29, s6, 0x80
	s_addc_u32 s9, s7, 0
	s_add_i32 s94, 0, 0x10000
	v_add_u32_e32 v138, s94, v141
	ds_read_b128 v[160:163], v138
	ds_read_b128 v[164:167], v138 offset:1024
	ds_read_b128 v[168:171], v138 offset:2048
	ds_read_b128 v[188:191], v138 offset:3072
	s_cmp_eq_u32 s69, s8
	s_cselect_b32 s8, s42, s29
	s_cselect_b32 s9, s43, s9
	s_cselect_b32 s53, s45, s11
	s_cselect_b32 s52, s44, s10
	v_lshl_add_u64 v[138:139], s[6:7], 0, v[136:137]
	s_add_i32 m0, s56, 0xc000
	ds_read_b128 v[192:195], v143
	ds_read_b128 v[196:199], v143 offset:1024
	ds_read_b128 v[200:203], v143 offset:2048
	ds_read_b128 v[204:207], v143 offset:3072
	ds_read_b128 v[208:211], v143 offset:4096
	ds_read_b128 v[212:215], v143 offset:5120
	ds_read_b128 v[216:219], v143 offset:6144
	ds_read_b128 v[220:223], v143 offset:7168
	global_load_lds_dwordx4 v[138:139], off
	v_lshl_add_u64 v[138:139], s[6:7], 0, v[134:135]
	s_add_i32 m0, s56, 0xe000
	s_nop 0
	global_load_lds_dwordx4 v[138:139], off
	s_waitcnt lgkmcnt(8)
	s_barrier
	s_waitcnt lgkmcnt(0)
	s_setprio 1
	v_mfma_f32_16x16x32_bf16 v[120:123], v[160:163], v[192:195], v[120:123]
	v_mfma_f32_16x16x32_bf16 v[112:115], v[168:171], v[192:195], v[112:115]
	v_mfma_f32_16x16x32_bf16 v[104:107], v[160:163], v[200:203], v[104:107]
	v_mfma_f32_16x16x32_bf16 v[96:99], v[168:171], v[200:203], v[96:99]
	v_mfma_f32_16x16x32_bf16 v[88:91], v[160:163], v[208:211], v[88:91]
	v_mfma_f32_16x16x32_bf16 v[80:83], v[168:171], v[208:211], v[80:83]
	v_mfma_f32_16x16x32_bf16 v[72:75], v[160:163], v[216:219], v[72:75]
	v_mfma_f32_16x16x32_bf16 v[64:67], v[168:171], v[216:219], v[64:67]
	v_mfma_f32_16x16x32_bf16 v[120:123], v[164:167], v[196:199], v[120:123]
	v_mfma_f32_16x16x32_bf16 v[112:115], v[188:191], v[196:199], v[112:115]
	v_mfma_f32_16x16x32_bf16 v[104:107], v[164:167], v[204:207], v[104:107]
	v_mfma_f32_16x16x32_bf16 v[96:99], v[188:191], v[204:207], v[96:99]
	v_mfma_f32_16x16x32_bf16 v[88:91], v[164:167], v[212:215], v[88:91]
	v_mfma_f32_16x16x32_bf16 v[80:83], v[188:191], v[212:215], v[80:83]
	v_mfma_f32_16x16x32_bf16 v[72:75], v[164:167], v[220:223], v[72:75]
	v_mfma_f32_16x16x32_bf16 v[64:67], v[188:191], v[220:223], v[64:67]
	s_setprio 0
	s_barrier
	s_add_i32 s29, 0, 0x14000
	v_add_u32_e32 v138, s29, v141
	s_add_i32 s94, s94, s55
	ds_read_b128 v[224:227], v138
	ds_read_b128 v[228:231], v138 offset:1024
	ds_read_b128 v[232:235], v138 offset:2048
	ds_read_b128 v[236:239], v138 offset:3072
	v_lshl_add_u64 v[138:139], s[52:53], 0, v[144:145]
	s_mov_b32 m0, s94
	v_lshl_add_u64 v[240:241], s[52:53], 0, v[128:129]
	global_load_lds_dwordx4 v[138:139], off
	s_add_i32 m0, s94, 0x2000
	s_nop 0
	global_load_lds_dwordx4 v[240:241], off
	s_barrier
	s_waitcnt lgkmcnt(0)
	s_setprio 1
	v_mfma_f32_16x16x32_bf16 v[124:127], v[224:227], v[192:195], v[124:127]
	v_mfma_f32_16x16x32_bf16 v[116:119], v[232:235], v[192:195], v[116:119]
	v_mfma_f32_16x16x32_bf16 v[108:111], v[224:227], v[200:203], v[108:111]
	v_mfma_f32_16x16x32_bf16 v[100:103], v[232:235], v[200:203], v[100:103]
	v_mfma_f32_16x16x32_bf16 v[92:95], v[224:227], v[208:211], v[92:95]
	v_mfma_f32_16x16x32_bf16 v[84:87], v[232:235], v[208:211], v[84:87]
	v_mfma_f32_16x16x32_bf16 v[76:79], v[224:227], v[216:219], v[76:79]
	v_mfma_f32_16x16x32_bf16 v[68:71], v[232:235], v[216:219], v[68:71]
	v_mfma_f32_16x16x32_bf16 v[124:127], v[228:231], v[196:199], v[124:127]
	v_mfma_f32_16x16x32_bf16 v[116:119], v[236:239], v[196:199], v[116:119]
	v_mfma_f32_16x16x32_bf16 v[108:111], v[228:231], v[204:207], v[108:111]
	v_mfma_f32_16x16x32_bf16 v[100:103], v[236:239], v[204:207], v[100:103]
	v_mfma_f32_16x16x32_bf16 v[92:95], v[228:231], v[212:215], v[92:95]
	v_mfma_f32_16x16x32_bf16 v[84:87], v[236:239], v[212:215], v[84:87]
	v_mfma_f32_16x16x32_bf16 v[76:79], v[228:231], v[220:223], v[76:79]
	v_mfma_f32_16x16x32_bf16 v[68:71], v[236:239], v[220:223], v[68:71]
	s_setprio 0
	s_mov_b32 m0, s56
	v_lshl_add_u64 v[242:243], s[8:9], 0, v[132:133]
	s_barrier
	ds_read_b128 v[192:195], v143 offset:16384
	ds_read_b128 v[196:199], v143 offset:17408
	ds_read_b128 v[200:203], v143 offset:18432
	ds_read_b128 v[204:207], v143 offset:19456
	ds_read_b128 v[208:211], v143 offset:20480
	ds_read_b128 v[212:215], v143 offset:21504
	ds_read_b128 v[216:219], v143 offset:22528
	ds_read_b128 v[220:223], v143 offset:23552
	global_load_lds_dwordx4 v[242:243], off
	v_lshl_add_u64 v[244:245], s[8:9], 0, v[130:131]
	s_mov_b32 m0, s57
	s_nop 0
	global_load_lds_dwordx4 v[244:245], off
	s_barrier
	s_waitcnt lgkmcnt(0)
	s_setprio 1
	v_mfma_f32_16x16x32_bf16 v[56:59], v[160:163], v[192:195], v[56:59]
	v_mfma_f32_16x16x32_bf16 v[48:51], v[168:171], v[192:195], v[48:51]
	v_mfma_f32_16x16x32_bf16 v[40:43], v[160:163], v[200:203], v[40:43]
	v_mfma_f32_16x16x32_bf16 v[32:35], v[168:171], v[200:203], v[32:35]
	v_mfma_f32_16x16x32_bf16 v[24:27], v[160:163], v[208:211], v[24:27]
	v_mfma_f32_16x16x32_bf16 v[16:19], v[168:171], v[208:211], v[16:19]
	v_mfma_f32_16x16x32_bf16 v[8:11], v[160:163], v[216:219], v[8:11]
	v_mfma_f32_16x16x32_bf16 v[0:3], v[168:171], v[216:219], v[0:3]
	v_mfma_f32_16x16x32_bf16 v[56:59], v[164:167], v[196:199], v[56:59]
	v_mfma_f32_16x16x32_bf16 v[48:51], v[188:191], v[196:199], v[48:51]
	v_mfma_f32_16x16x32_bf16 v[40:43], v[164:167], v[204:207], v[40:43]
	v_mfma_f32_16x16x32_bf16 v[32:35], v[188:191], v[204:207], v[32:35]
	v_mfma_f32_16x16x32_bf16 v[24:27], v[164:167], v[212:215], v[24:27]
	v_mfma_f32_16x16x32_bf16 v[16:19], v[188:191], v[212:215], v[16:19]
	v_mfma_f32_16x16x32_bf16 v[8:11], v[164:167], v[220:223], v[8:11]
	v_mfma_f32_16x16x32_bf16 v[0:3], v[188:191], v[220:223], v[0:3]
	s_setprio 0
	s_barrier
	s_add_u32 s52, s52, s4
	s_addc_u32 s53, s53, s5
	s_add_i32 s29, s29, s55
	v_lshl_add_u64 v[246:247], s[52:53], 0, v[144:145]
	s_mov_b32 m0, s29
	v_lshl_add_u64 v[248:249], s[52:53], 0, v[128:129]
	global_load_lds_dwordx4 v[246:247], off
	s_add_i32 m0, s29, 0x2000
	s_nop 0
	global_load_lds_dwordx4 v[248:249], off
	s_waitcnt vmcnt(6)
	s_barrier
	s_setprio 1
	v_mfma_f32_16x16x32_bf16 v[60:63], v[224:227], v[192:195], v[60:63]
	v_mfma_f32_16x16x32_bf16 v[52:55], v[232:235], v[192:195], v[52:55]
	v_mfma_f32_16x16x32_bf16 v[44:47], v[224:227], v[200:203], v[44:47]
	v_mfma_f32_16x16x32_bf16 v[36:39], v[232:235], v[200:203], v[36:39]
	v_mfma_f32_16x16x32_bf16 v[28:31], v[224:227], v[208:211], v[28:31]
	v_mfma_f32_16x16x32_bf16 v[20:23], v[232:235], v[208:211], v[20:23]
	v_mfma_f32_16x16x32_bf16 v[12:15], v[224:227], v[216:219], v[12:15]
	v_mfma_f32_16x16x32_bf16 v[4:7], v[232:235], v[216:219], v[4:7]
	v_mfma_f32_16x16x32_bf16 v[60:63], v[228:231], v[196:199], v[60:63]
	v_mfma_f32_16x16x32_bf16 v[52:55], v[236:239], v[196:199], v[52:55]
	v_mfma_f32_16x16x32_bf16 v[44:47], v[228:231], v[204:207], v[44:47]
	v_mfma_f32_16x16x32_bf16 v[36:39], v[236:239], v[204:207], v[36:39]
	v_mfma_f32_16x16x32_bf16 v[28:31], v[228:231], v[212:215], v[28:31]
	v_mfma_f32_16x16x32_bf16 v[20:23], v[236:239], v[212:215], v[20:23]
	v_mfma_f32_16x16x32_bf16 v[12:15], v[228:231], v[220:223], v[12:15]
	v_mfma_f32_16x16x32_bf16 v[4:7], v[236:239], v[220:223], v[4:7]
	s_setprio 0
	s_add_i32 s29, 0, 0x18000
	v_add_u32_e32 v188, s29, v141
	s_barrier
	ds_read_b128 v[160:163], v188
	ds_read_b128 v[164:167], v188 offset:1024
	ds_read_b128 v[168:171], v188 offset:2048
	ds_read_b128 v[188:191], v188 offset:3072
	s_add_u32 s8, s8, s4
	s_addc_u32 s9, s9, s5
	s_mov_b32 m0, s58
	v_lshl_add_u64 v[224:225], s[8:9], 0, v[132:133]
	ds_read_b128 v[192:195], v143 offset:32768
	ds_read_b128 v[196:199], v143 offset:33792
	ds_read_b128 v[200:203], v143 offset:34816
	ds_read_b128 v[204:207], v143 offset:35840
	ds_read_b128 v[208:211], v143 offset:36864
	ds_read_b128 v[212:215], v143 offset:37888
	ds_read_b128 v[216:219], v143 offset:38912
	ds_read_b128 v[220:223], v143 offset:39936
	global_load_lds_dwordx4 v[224:225], off
	v_lshl_add_u64 v[224:225], s[8:9], 0, v[130:131]
	s_mov_b32 m0, s59
	s_nop 0
	global_load_lds_dwordx4 v[224:225], off
	s_waitcnt lgkmcnt(8)
	s_barrier
	s_waitcnt lgkmcnt(0)
	s_setprio 1
	v_mfma_f32_16x16x32_bf16 v[120:123], v[160:163], v[192:195], v[120:123]
	v_mfma_f32_16x16x32_bf16 v[112:115], v[168:171], v[192:195], v[112:115]
	v_mfma_f32_16x16x32_bf16 v[104:107], v[160:163], v[200:203], v[104:107]
	v_mfma_f32_16x16x32_bf16 v[96:99], v[168:171], v[200:203], v[96:99]
	v_mfma_f32_16x16x32_bf16 v[88:91], v[160:163], v[208:211], v[88:91]
	v_mfma_f32_16x16x32_bf16 v[80:83], v[168:171], v[208:211], v[80:83]
	v_mfma_f32_16x16x32_bf16 v[72:75], v[160:163], v[216:219], v[72:75]
	v_mfma_f32_16x16x32_bf16 v[64:67], v[168:171], v[216:219], v[64:67]
	v_mfma_f32_16x16x32_bf16 v[120:123], v[164:167], v[196:199], v[120:123]
	v_mfma_f32_16x16x32_bf16 v[112:115], v[188:191], v[196:199], v[112:115]
	v_mfma_f32_16x16x32_bf16 v[104:107], v[164:167], v[204:207], v[104:107]
	v_mfma_f32_16x16x32_bf16 v[96:99], v[188:191], v[204:207], v[96:99]
	v_mfma_f32_16x16x32_bf16 v[88:91], v[164:167], v[212:215], v[88:91]
	v_mfma_f32_16x16x32_bf16 v[80:83], v[188:191], v[212:215], v[80:83]
	v_mfma_f32_16x16x32_bf16 v[72:75], v[164:167], v[220:223], v[72:75]
	v_mfma_f32_16x16x32_bf16 v[64:67], v[188:191], v[220:223], v[64:67]
	s_setprio 0
	s_barrier
	s_add_i32 s8, 0, 0x1c000
	s_add_i32 s9, s29, s55
	v_add_u32_e32 v236, s8, v141
	v_lshl_add_u64 v[138:139], v[138:139], 0, s[82:83]
	s_mov_b32 m0, s9
	ds_read_b128 v[224:227], v236
	ds_read_b128 v[228:231], v236 offset:1024
	ds_read_b128 v[232:235], v236 offset:2048
	ds_read_b128 v[236:239], v236 offset:3072
	global_load_lds_dwordx4 v[138:139], off
	v_lshl_add_u64 v[138:139], v[240:241], 0, s[82:83]
	s_add_i32 m0, s9, 0x2000
	s_nop 0
	global_load_lds_dwordx4 v[138:139], off
	s_barrier
	s_waitcnt lgkmcnt(0)
	s_setprio 1
	v_mfma_f32_16x16x32_bf16 v[124:127], v[224:227], v[192:195], v[124:127]
	v_mfma_f32_16x16x32_bf16 v[116:119], v[232:235], v[192:195], v[116:119]
	v_mfma_f32_16x16x32_bf16 v[108:111], v[224:227], v[200:203], v[108:111]
	v_mfma_f32_16x16x32_bf16 v[100:103], v[232:235], v[200:203], v[100:103]
	v_mfma_f32_16x16x32_bf16 v[92:95], v[224:227], v[208:211], v[92:95]
	v_mfma_f32_16x16x32_bf16 v[84:87], v[232:235], v[208:211], v[84:87]
	v_mfma_f32_16x16x32_bf16 v[76:79], v[224:227], v[216:219], v[76:79]
	v_mfma_f32_16x16x32_bf16 v[68:71], v[232:235], v[216:219], v[68:71]
	v_mfma_f32_16x16x32_bf16 v[124:127], v[228:231], v[196:199], v[124:127]
	v_mfma_f32_16x16x32_bf16 v[116:119], v[236:239], v[196:199], v[116:119]
	v_mfma_f32_16x16x32_bf16 v[108:111], v[228:231], v[204:207], v[108:111]
	v_mfma_f32_16x16x32_bf16 v[100:103], v[236:239], v[204:207], v[100:103]
	v_mfma_f32_16x16x32_bf16 v[92:95], v[228:231], v[212:215], v[92:95]
	v_mfma_f32_16x16x32_bf16 v[84:87], v[236:239], v[212:215], v[84:87]
	v_mfma_f32_16x16x32_bf16 v[76:79], v[228:231], v[220:223], v[76:79]
	v_mfma_f32_16x16x32_bf16 v[68:71], v[236:239], v[220:223], v[68:71]
	s_setprio 0
	s_mov_b32 m0, s61
	v_lshl_add_u64 v[138:139], v[242:243], 0, s[82:83]
	s_barrier
	ds_read_b128 v[192:195], v143 offset:49152
	ds_read_b128 v[196:199], v143 offset:50176
	ds_read_b128 v[200:203], v143 offset:51200
	ds_read_b128 v[204:207], v143 offset:52224
	ds_read_b128 v[208:211], v143 offset:53248
	ds_read_b128 v[212:215], v143 offset:54272
	ds_read_b128 v[216:219], v143 offset:55296
	ds_read_b128 v[220:223], v143 offset:56320
	global_load_lds_dwordx4 v[138:139], off
	v_lshl_add_u64 v[138:139], v[244:245], 0, s[82:83]
	s_mov_b32 m0, s68
	s_nop 0
	global_load_lds_dwordx4 v[138:139], off
	s_barrier
	s_waitcnt lgkmcnt(0)
	s_setprio 1
	v_mfma_f32_16x16x32_bf16 v[56:59], v[160:163], v[192:195], v[56:59]
	v_mfma_f32_16x16x32_bf16 v[48:51], v[168:171], v[192:195], v[48:51]
	v_mfma_f32_16x16x32_bf16 v[40:43], v[160:163], v[200:203], v[40:43]
	v_mfma_f32_16x16x32_bf16 v[32:35], v[168:171], v[200:203], v[32:35]
	v_mfma_f32_16x16x32_bf16 v[24:27], v[160:163], v[208:211], v[24:27]
	v_mfma_f32_16x16x32_bf16 v[16:19], v[168:171], v[208:211], v[16:19]
	v_mfma_f32_16x16x32_bf16 v[8:11], v[160:163], v[216:219], v[8:11]
	v_mfma_f32_16x16x32_bf16 v[0:3], v[168:171], v[216:219], v[0:3]
	v_mfma_f32_16x16x32_bf16 v[56:59], v[164:167], v[196:199], v[56:59]
	v_mfma_f32_16x16x32_bf16 v[48:51], v[188:191], v[196:199], v[48:51]
	v_mfma_f32_16x16x32_bf16 v[40:43], v[164:167], v[204:207], v[40:43]
	v_mfma_f32_16x16x32_bf16 v[32:35], v[188:191], v[204:207], v[32:35]
	v_mfma_f32_16x16x32_bf16 v[24:27], v[164:167], v[212:215], v[24:27]
	v_mfma_f32_16x16x32_bf16 v[16:19], v[188:191], v[212:215], v[16:19]
	v_mfma_f32_16x16x32_bf16 v[8:11], v[164:167], v[220:223], v[8:11]
	v_mfma_f32_16x16x32_bf16 v[0:3], v[188:191], v[220:223], v[0:3]
	s_setprio 0
	s_barrier
	s_add_i32 s8, s8, s55
	v_lshl_add_u64 v[138:139], v[246:247], 0, s[82:83]
	s_mov_b32 m0, s8
	s_nop 0
	global_load_lds_dwordx4 v[138:139], off
	v_lshl_add_u64 v[138:139], v[248:249], 0, s[82:83]
	s_add_i32 m0, s8, 0x2000
	s_nop 0
	global_load_lds_dwordx4 v[138:139], off
	s_waitcnt vmcnt(6)
	s_barrier
	s_setprio 1
	v_mfma_f32_16x16x32_bf16 v[60:63], v[224:227], v[192:195], v[60:63]
	v_mfma_f32_16x16x32_bf16 v[52:55], v[232:235], v[192:195], v[52:55]
	v_mfma_f32_16x16x32_bf16 v[44:47], v[224:227], v[200:203], v[44:47]
	v_mfma_f32_16x16x32_bf16 v[36:39], v[232:235], v[200:203], v[36:39]
	v_mfma_f32_16x16x32_bf16 v[28:31], v[224:227], v[208:211], v[28:31]
	v_mfma_f32_16x16x32_bf16 v[20:23], v[232:235], v[208:211], v[20:23]
	v_mfma_f32_16x16x32_bf16 v[12:15], v[224:227], v[216:219], v[12:15]
	v_mfma_f32_16x16x32_bf16 v[4:7], v[232:235], v[216:219], v[4:7]
	v_mfma_f32_16x16x32_bf16 v[60:63], v[228:231], v[196:199], v[60:63]
	v_mfma_f32_16x16x32_bf16 v[52:55], v[236:239], v[196:199], v[52:55]
	v_mfma_f32_16x16x32_bf16 v[44:47], v[228:231], v[204:207], v[44:47]
	v_mfma_f32_16x16x32_bf16 v[36:39], v[236:239], v[204:207], v[36:39]
	v_mfma_f32_16x16x32_bf16 v[28:31], v[228:231], v[212:215], v[28:31]
	v_mfma_f32_16x16x32_bf16 v[20:23], v[236:239], v[212:215], v[20:23]
	v_mfma_f32_16x16x32_bf16 v[12:15], v[228:231], v[220:223], v[12:15]
	v_mfma_f32_16x16x32_bf16 v[4:7], v[236:239], v[220:223], v[4:7]
	s_setprio 0
	s_add_u32 s10, s10, 0x100
	s_addc_u32 s11, s11, 0
	s_add_u32 s6, s6, 0x100
	s_addc_u32 s7, s7, 0
	s_cmp_ge_i32 s28, s60
	s_mov_b32 s8, s28
	s_barrier
	s_cbranch_scc0 .LBB0_204
	s_branch .LBB0_195

.LBB0_277:
	s_add_i32 s28, s8, 2
	s_add_u32 s29, s6, 0x80
	s_addc_u32 s9, s7, 0
	s_add_i32 s91, 0, 0x10000
	v_add_u32_e32 v142, s91, v189
	ds_read_b128 v[134:137], v142
	ds_read_b128 v[138:141], v142 offset:1024
	ds_read_b128 v[160:163], v142 offset:2048
	ds_read_b128 v[164:167], v142 offset:3072
	s_cmp_eq_u32 s61, s8
	s_cselect_b32 s8, s44, s29
	s_cselect_b32 s9, s45, s9
	s_cselect_b32 s51, s47, s11
	s_cselect_b32 s50, s46, s10
	v_lshl_add_u64 v[142:143], s[6:7], 0, v[132:133]
	s_add_i32 m0, s54, 0xc000
	ds_read_b128 v[168:171], v191
	ds_read_b128 v[192:195], v191 offset:1024
	ds_read_b128 v[196:199], v191 offset:2048
	ds_read_b128 v[200:203], v191 offset:3072
	ds_read_b128 v[204:207], v191 offset:4096
	ds_read_b128 v[208:211], v191 offset:5120
	ds_read_b128 v[212:215], v191 offset:6144
	ds_read_b128 v[216:219], v191 offset:7168
	global_load_lds_dwordx4 v[142:143], off
	v_lshl_add_u64 v[142:143], s[6:7], 0, v[130:131]
	s_add_i32 m0, s54, 0xe000
	s_nop 0
	global_load_lds_dwordx4 v[142:143], off
	s_waitcnt lgkmcnt(8)
	s_barrier
	s_waitcnt lgkmcnt(0)
	s_setprio 1
	v_mfma_f32_16x16x32_bf16 v[124:127], v[134:137], v[168:171], v[124:127]
	v_mfma_f32_16x16x32_bf16 v[120:123], v[160:163], v[168:171], v[120:123]
	v_mfma_f32_16x16x32_bf16 v[108:111], v[134:137], v[196:199], v[108:111]
	v_mfma_f32_16x16x32_bf16 v[104:107], v[160:163], v[196:199], v[104:107]
	v_mfma_f32_16x16x32_bf16 v[92:95], v[134:137], v[204:207], v[92:95]
	v_mfma_f32_16x16x32_bf16 v[88:91], v[160:163], v[204:207], v[88:91]
	v_mfma_f32_16x16x32_bf16 v[76:79], v[134:137], v[212:215], v[76:79]
	v_mfma_f32_16x16x32_bf16 v[72:75], v[160:163], v[212:215], v[72:75]
	v_mfma_f32_16x16x32_bf16 v[124:127], v[138:141], v[192:195], v[124:127]
	v_mfma_f32_16x16x32_bf16 v[120:123], v[164:167], v[192:195], v[120:123]
	v_mfma_f32_16x16x32_bf16 v[108:111], v[138:141], v[200:203], v[108:111]
	v_mfma_f32_16x16x32_bf16 v[104:107], v[164:167], v[200:203], v[104:107]
	v_mfma_f32_16x16x32_bf16 v[92:95], v[138:141], v[208:211], v[92:95]
	v_mfma_f32_16x16x32_bf16 v[88:91], v[164:167], v[208:211], v[88:91]
	v_mfma_f32_16x16x32_bf16 v[76:79], v[138:141], v[216:219], v[76:79]
	v_mfma_f32_16x16x32_bf16 v[72:75], v[164:167], v[216:219], v[72:75]
	s_setprio 0
	s_barrier
	s_add_i32 s29, 0, 0x14000
	v_add_u32_e32 v142, s29, v189
	s_add_i32 s91, s91, s53
	ds_read_b128 v[220:223], v142
	ds_read_b128 v[224:227], v142 offset:1024
	ds_read_b128 v[228:231], v142 offset:2048
	ds_read_b128 v[232:235], v142 offset:3072
	v_lshl_add_u64 v[142:143], s[50:51], 0, v[144:145]
	s_mov_b32 m0, s91
	v_lshl_add_u64 v[236:237], s[50:51], 0, v[128:129]
	global_load_lds_dwordx4 v[142:143], off
	s_add_i32 m0, s91, 0x2000
	s_nop 0
	global_load_lds_dwordx4 v[236:237], off
	s_barrier
	s_waitcnt lgkmcnt(0)
	s_setprio 1
	v_mfma_f32_16x16x32_bf16 v[116:119], v[220:223], v[168:171], v[116:119]
	v_mfma_f32_16x16x32_bf16 v[112:115], v[228:231], v[168:171], v[112:115]
	v_mfma_f32_16x16x32_bf16 v[100:103], v[220:223], v[196:199], v[100:103]
	v_mfma_f32_16x16x32_bf16 v[96:99], v[228:231], v[196:199], v[96:99]
	v_mfma_f32_16x16x32_bf16 v[84:87], v[220:223], v[204:207], v[84:87]
	v_mfma_f32_16x16x32_bf16 v[80:83], v[228:231], v[204:207], v[80:83]
	v_mfma_f32_16x16x32_bf16 v[68:71], v[220:223], v[212:215], v[68:71]
	v_mfma_f32_16x16x32_bf16 v[64:67], v[228:231], v[212:215], v[64:67]
	v_mfma_f32_16x16x32_bf16 v[116:119], v[224:227], v[192:195], v[116:119]
	v_mfma_f32_16x16x32_bf16 v[112:115], v[232:235], v[192:195], v[112:115]
	v_mfma_f32_16x16x32_bf16 v[100:103], v[224:227], v[200:203], v[100:103]
	v_mfma_f32_16x16x32_bf16 v[96:99], v[232:235], v[200:203], v[96:99]
	v_mfma_f32_16x16x32_bf16 v[84:87], v[224:227], v[208:211], v[84:87]
	v_mfma_f32_16x16x32_bf16 v[80:83], v[232:235], v[208:211], v[80:83]
	v_mfma_f32_16x16x32_bf16 v[68:71], v[224:227], v[216:219], v[68:71]
	v_mfma_f32_16x16x32_bf16 v[64:67], v[232:235], v[216:219], v[64:67]
	s_setprio 0
	s_mov_b32 m0, s54
	v_lshl_add_u64 v[238:239], s[8:9], 0, v[144:145]
	s_barrier
	ds_read_b128 v[168:171], v191 offset:16384
	ds_read_b128 v[192:195], v191 offset:17408
	ds_read_b128 v[196:199], v191 offset:18432
	ds_read_b128 v[200:203], v191 offset:19456
	ds_read_b128 v[204:207], v191 offset:20480
	ds_read_b128 v[208:211], v191 offset:21504
	ds_read_b128 v[212:215], v191 offset:22528
	ds_read_b128 v[216:219], v191 offset:23552
	global_load_lds_dwordx4 v[238:239], off
	v_lshl_add_u64 v[240:241], s[8:9], 0, v[128:129]
	s_mov_b32 m0, s55
	s_nop 0
	global_load_lds_dwordx4 v[240:241], off
	s_barrier
	s_waitcnt lgkmcnt(0)
	s_setprio 1
	v_mfma_f32_16x16x32_bf16 v[60:63], v[134:137], v[168:171], v[60:63]
	v_mfma_f32_16x16x32_bf16 v[56:59], v[160:163], v[168:171], v[56:59]
	v_mfma_f32_16x16x32_bf16 v[44:47], v[134:137], v[196:199], v[44:47]
	v_mfma_f32_16x16x32_bf16 v[40:43], v[160:163], v[196:199], v[40:43]
	v_mfma_f32_16x16x32_bf16 v[28:31], v[134:137], v[204:207], v[28:31]
	v_mfma_f32_16x16x32_bf16 v[24:27], v[160:163], v[204:207], v[24:27]
	v_mfma_f32_16x16x32_bf16 v[12:15], v[134:137], v[212:215], v[12:15]
	v_mfma_f32_16x16x32_bf16 v[8:11], v[160:163], v[212:215], v[8:11]
	v_mfma_f32_16x16x32_bf16 v[60:63], v[138:141], v[192:195], v[60:63]
	v_mfma_f32_16x16x32_bf16 v[56:59], v[164:167], v[192:195], v[56:59]
	v_mfma_f32_16x16x32_bf16 v[44:47], v[138:141], v[200:203], v[44:47]
	v_mfma_f32_16x16x32_bf16 v[40:43], v[164:167], v[200:203], v[40:43]
	v_mfma_f32_16x16x32_bf16 v[28:31], v[138:141], v[208:211], v[28:31]
	v_mfma_f32_16x16x32_bf16 v[24:27], v[164:167], v[208:211], v[24:27]
	v_mfma_f32_16x16x32_bf16 v[12:15], v[138:141], v[216:219], v[12:15]
	v_mfma_f32_16x16x32_bf16 v[8:11], v[164:167], v[216:219], v[8:11]
	s_setprio 0
	s_barrier
	s_add_u32 s50, s50, s4
	s_addc_u32 s51, s51, s5
	s_add_i32 s29, s29, s53
	v_lshl_add_u64 v[242:243], s[50:51], 0, v[144:145]
	s_mov_b32 m0, s29
	v_lshl_add_u64 v[244:245], s[50:51], 0, v[128:129]
	global_load_lds_dwordx4 v[242:243], off
	s_add_i32 m0, s29, 0x2000
	s_nop 0
	global_load_lds_dwordx4 v[244:245], off
	s_waitcnt vmcnt(6)
	s_barrier
	s_setprio 1
	v_mfma_f32_16x16x32_bf16 v[52:55], v[220:223], v[168:171], v[52:55]
	v_mfma_f32_16x16x32_bf16 v[48:51], v[228:231], v[168:171], v[48:51]
	v_mfma_f32_16x16x32_bf16 v[36:39], v[220:223], v[196:199], v[36:39]
	v_mfma_f32_16x16x32_bf16 v[32:35], v[228:231], v[196:199], v[32:35]
	v_mfma_f32_16x16x32_bf16 v[20:23], v[220:223], v[204:207], v[20:23]
	v_mfma_f32_16x16x32_bf16 v[16:19], v[228:231], v[204:207], v[16:19]
	v_mfma_f32_16x16x32_bf16 v[4:7], v[220:223], v[212:215], v[4:7]
	v_mfma_f32_16x16x32_bf16 v[0:3], v[228:231], v[212:215], v[0:3]
	v_mfma_f32_16x16x32_bf16 v[52:55], v[224:227], v[192:195], v[52:55]
	v_mfma_f32_16x16x32_bf16 v[48:51], v[232:235], v[192:195], v[48:51]
	v_mfma_f32_16x16x32_bf16 v[36:39], v[224:227], v[200:203], v[36:39]
	v_mfma_f32_16x16x32_bf16 v[32:35], v[232:235], v[200:203], v[32:35]
	v_mfma_f32_16x16x32_bf16 v[20:23], v[224:227], v[208:211], v[20:23]
	v_mfma_f32_16x16x32_bf16 v[16:19], v[232:235], v[208:211], v[16:19]
	v_mfma_f32_16x16x32_bf16 v[4:7], v[224:227], v[216:219], v[4:7]
	v_mfma_f32_16x16x32_bf16 v[0:3], v[232:235], v[216:219], v[0:3]
	s_setprio 0
	s_add_i32 s29, 0, 0x18000
	v_add_u32_e32 v164, s29, v189
	s_barrier
	ds_read_b128 v[134:137], v164
	ds_read_b128 v[138:141], v164 offset:1024
	ds_read_b128 v[160:163], v164 offset:2048
	ds_read_b128 v[164:167], v164 offset:3072
	s_add_u32 s8, s8, s4
	s_addc_u32 s9, s9, s5
	s_mov_b32 m0, s56
	v_lshl_add_u64 v[220:221], s[8:9], 0, v[144:145]
	ds_read_b128 v[168:171], v191 offset:32768
	ds_read_b128 v[192:195], v191 offset:33792
	ds_read_b128 v[196:199], v191 offset:34816
	ds_read_b128 v[200:203], v191 offset:35840
	ds_read_b128 v[204:207], v191 offset:36864
	ds_read_b128 v[208:211], v191 offset:37888
	ds_read_b128 v[212:215], v191 offset:38912
	ds_read_b128 v[216:219], v191 offset:39936
	global_load_lds_dwordx4 v[220:221], off
	v_lshl_add_u64 v[220:221], s[8:9], 0, v[128:129]
	s_mov_b32 m0, s57
	s_nop 0
	global_load_lds_dwordx4 v[220:221], off
	s_waitcnt lgkmcnt(8)
	s_barrier
	s_waitcnt lgkmcnt(0)
	s_setprio 1
	v_mfma_f32_16x16x32_bf16 v[124:127], v[134:137], v[168:171], v[124:127]
	v_mfma_f32_16x16x32_bf16 v[120:123], v[160:163], v[168:171], v[120:123]
	v_mfma_f32_16x16x32_bf16 v[108:111], v[134:137], v[196:199], v[108:111]
	v_mfma_f32_16x16x32_bf16 v[104:107], v[160:163], v[196:199], v[104:107]
	v_mfma_f32_16x16x32_bf16 v[92:95], v[134:137], v[204:207], v[92:95]
	v_mfma_f32_16x16x32_bf16 v[88:91], v[160:163], v[204:207], v[88:91]
	v_mfma_f32_16x16x32_bf16 v[76:79], v[134:137], v[212:215], v[76:79]
	v_mfma_f32_16x16x32_bf16 v[72:75], v[160:163], v[212:215], v[72:75]
	v_mfma_f32_16x16x32_bf16 v[124:127], v[138:141], v[192:195], v[124:127]
	v_mfma_f32_16x16x32_bf16 v[120:123], v[164:167], v[192:195], v[120:123]
	v_mfma_f32_16x16x32_bf16 v[108:111], v[138:141], v[200:203], v[108:111]
	v_mfma_f32_16x16x32_bf16 v[104:107], v[164:167], v[200:203], v[104:107]
	v_mfma_f32_16x16x32_bf16 v[92:95], v[138:141], v[208:211], v[92:95]
	v_mfma_f32_16x16x32_bf16 v[88:91], v[164:167], v[208:211], v[88:91]
	v_mfma_f32_16x16x32_bf16 v[76:79], v[138:141], v[216:219], v[76:79]
	v_mfma_f32_16x16x32_bf16 v[72:75], v[164:167], v[216:219], v[72:75]
	s_setprio 0
	s_barrier
	s_add_i32 s8, 0, 0x1c000
	s_add_i32 s9, s29, s53
	v_add_u32_e32 v232, s8, v189
	v_lshl_add_u64 v[142:143], v[142:143], 0, s[82:83]
	s_mov_b32 m0, s9
	ds_read_b128 v[220:223], v232
	ds_read_b128 v[224:227], v232 offset:1024
	ds_read_b128 v[228:231], v232 offset:2048
	ds_read_b128 v[232:235], v232 offset:3072
	global_load_lds_dwordx4 v[142:143], off
	v_lshl_add_u64 v[142:143], v[236:237], 0, s[82:83]
	s_add_i32 m0, s9, 0x2000
	s_nop 0
	global_load_lds_dwordx4 v[142:143], off
	s_barrier
	s_waitcnt lgkmcnt(0)
	s_setprio 1
	v_mfma_f32_16x16x32_bf16 v[116:119], v[220:223], v[168:171], v[116:119]
	v_mfma_f32_16x16x32_bf16 v[112:115], v[228:231], v[168:171], v[112:115]
	v_mfma_f32_16x16x32_bf16 v[100:103], v[220:223], v[196:199], v[100:103]
	v_mfma_f32_16x16x32_bf16 v[96:99], v[228:231], v[196:199], v[96:99]
	v_mfma_f32_16x16x32_bf16 v[84:87], v[220:223], v[204:207], v[84:87]
	v_mfma_f32_16x16x32_bf16 v[80:83], v[228:231], v[204:207], v[80:83]
	v_mfma_f32_16x16x32_bf16 v[68:71], v[220:223], v[212:215], v[68:71]
	v_mfma_f32_16x16x32_bf16 v[64:67], v[228:231], v[212:215], v[64:67]
	v_mfma_f32_16x16x32_bf16 v[116:119], v[224:227], v[192:195], v[116:119]
	v_mfma_f32_16x16x32_bf16 v[112:115], v[232:235], v[192:195], v[112:115]
	v_mfma_f32_16x16x32_bf16 v[100:103], v[224:227], v[200:203], v[100:103]
	v_mfma_f32_16x16x32_bf16 v[96:99], v[232:235], v[200:203], v[96:99]
	v_mfma_f32_16x16x32_bf16 v[84:87], v[224:227], v[208:211], v[84:87]
	v_mfma_f32_16x16x32_bf16 v[80:83], v[232:235], v[208:211], v[80:83]
	v_mfma_f32_16x16x32_bf16 v[68:71], v[224:227], v[216:219], v[68:71]
	v_mfma_f32_16x16x32_bf16 v[64:67], v[232:235], v[216:219], v[64:67]
	s_setprio 0
	s_mov_b32 m0, s59
	v_lshl_add_u64 v[142:143], v[238:239], 0, s[82:83]
	s_barrier
	ds_read_b128 v[168:171], v191 offset:49152
	ds_read_b128 v[192:195], v191 offset:50176
	ds_read_b128 v[196:199], v191 offset:51200
	ds_read_b128 v[200:203], v191 offset:52224
	ds_read_b128 v[204:207], v191 offset:53248
	ds_read_b128 v[208:211], v191 offset:54272
	ds_read_b128 v[212:215], v191 offset:55296
	ds_read_b128 v[216:219], v191 offset:56320
	global_load_lds_dwordx4 v[142:143], off
	v_lshl_add_u64 v[142:143], v[240:241], 0, s[82:83]
	s_mov_b32 m0, s60
	s_nop 0
	global_load_lds_dwordx4 v[142:143], off
	s_barrier
	s_waitcnt lgkmcnt(0)
	s_setprio 1
	v_mfma_f32_16x16x32_bf16 v[60:63], v[134:137], v[168:171], v[60:63]
	v_mfma_f32_16x16x32_bf16 v[56:59], v[160:163], v[168:171], v[56:59]
	v_mfma_f32_16x16x32_bf16 v[44:47], v[134:137], v[196:199], v[44:47]
	v_mfma_f32_16x16x32_bf16 v[40:43], v[160:163], v[196:199], v[40:43]
	v_mfma_f32_16x16x32_bf16 v[28:31], v[134:137], v[204:207], v[28:31]
	v_mfma_f32_16x16x32_bf16 v[24:27], v[160:163], v[204:207], v[24:27]
	v_mfma_f32_16x16x32_bf16 v[12:15], v[134:137], v[212:215], v[12:15]
	v_mfma_f32_16x16x32_bf16 v[8:11], v[160:163], v[212:215], v[8:11]
	v_mfma_f32_16x16x32_bf16 v[60:63], v[138:141], v[192:195], v[60:63]
	v_mfma_f32_16x16x32_bf16 v[56:59], v[164:167], v[192:195], v[56:59]
	v_mfma_f32_16x16x32_bf16 v[44:47], v[138:141], v[200:203], v[44:47]
	v_mfma_f32_16x16x32_bf16 v[40:43], v[164:167], v[200:203], v[40:43]
	v_mfma_f32_16x16x32_bf16 v[28:31], v[138:141], v[208:211], v[28:31]
	v_mfma_f32_16x16x32_bf16 v[24:27], v[164:167], v[208:211], v[24:27]
	v_mfma_f32_16x16x32_bf16 v[12:15], v[138:141], v[216:219], v[12:15]
	v_mfma_f32_16x16x32_bf16 v[8:11], v[164:167], v[216:219], v[8:11]
	s_setprio 0
	s_barrier
	s_add_i32 s8, s8, s53
	v_lshl_add_u64 v[134:135], v[242:243], 0, s[82:83]
	s_mov_b32 m0, s8
	s_nop 0
	global_load_lds_dwordx4 v[134:135], off
	v_lshl_add_u64 v[134:135], v[244:245], 0, s[82:83]
	s_add_i32 m0, s8, 0x2000
	s_nop 0
	global_load_lds_dwordx4 v[134:135], off
	s_waitcnt vmcnt(6)
	s_barrier
	s_setprio 1
	v_mfma_f32_16x16x32_bf16 v[52:55], v[220:223], v[168:171], v[52:55]
	v_mfma_f32_16x16x32_bf16 v[48:51], v[228:231], v[168:171], v[48:51]
	v_mfma_f32_16x16x32_bf16 v[36:39], v[220:223], v[196:199], v[36:39]
	v_mfma_f32_16x16x32_bf16 v[32:35], v[228:231], v[196:199], v[32:35]
	v_mfma_f32_16x16x32_bf16 v[20:23], v[220:223], v[204:207], v[20:23]
	v_mfma_f32_16x16x32_bf16 v[16:19], v[228:231], v[204:207], v[16:19]
	v_mfma_f32_16x16x32_bf16 v[4:7], v[220:223], v[212:215], v[4:7]
	v_mfma_f32_16x16x32_bf16 v[0:3], v[228:231], v[212:215], v[0:3]
	v_mfma_f32_16x16x32_bf16 v[52:55], v[224:227], v[192:195], v[52:55]
	v_mfma_f32_16x16x32_bf16 v[48:51], v[232:235], v[192:195], v[48:51]
	v_mfma_f32_16x16x32_bf16 v[36:39], v[224:227], v[200:203], v[36:39]
	v_mfma_f32_16x16x32_bf16 v[32:35], v[232:235], v[200:203], v[32:35]
	v_mfma_f32_16x16x32_bf16 v[20:23], v[224:227], v[208:211], v[20:23]
	v_mfma_f32_16x16x32_bf16 v[16:19], v[232:235], v[208:211], v[16:19]
	v_mfma_f32_16x16x32_bf16 v[4:7], v[224:227], v[216:219], v[4:7]
	v_mfma_f32_16x16x32_bf16 v[0:3], v[232:235], v[216:219], v[0:3]
	s_setprio 0
	s_add_u32 s10, s10, 0x100
	s_addc_u32 s11, s11, 0
	s_add_u32 s6, s6, 0x100
	s_addc_u32 s7, s7, 0
	s_cmp_ge_i32 s28, s58
	s_mov_b32 s8, s28
	s_barrier
	s_cbranch_scc0 .LBB0_277
	s_branch .LBB0_264

.LBB0_405:
	s_add_i32 s28, s8, 2
	s_add_u32 s29, s6, 0x80
	s_addc_u32 s9, s7, 0
	s_add_i32 s71, 0, 0x10000
	v_add_u32_e32 v142, s71, v139
	ds_read_b128 v[160:163], v142
	ds_read_b128 v[164:167], v142 offset:1024
	ds_read_b128 v[168:171], v142 offset:2048
	ds_read_b128 v[188:191], v142 offset:3072
	s_cmp_eq_u32 s59, s8
	s_cselect_b32 s8, s44, s29
	s_cselect_b32 s9, s45, s9
	s_cselect_b32 s49, s47, s11
	s_cselect_b32 s48, s46, s10
	v_lshl_add_u64 v[142:143], s[6:7], 0, v[136:137]
	s_add_i32 m0, s52, 0xc000
	ds_read_b128 v[192:195], v141
	ds_read_b128 v[196:199], v141 offset:1024
	ds_read_b128 v[200:203], v141 offset:2048
	ds_read_b128 v[204:207], v141 offset:3072
	ds_read_b128 v[208:211], v141 offset:4096
	ds_read_b128 v[212:215], v141 offset:5120
	ds_read_b128 v[216:219], v141 offset:6144
	ds_read_b128 v[220:223], v141 offset:7168
	global_load_lds_dwordx4 v[142:143], off
	v_lshl_add_u64 v[142:143], s[6:7], 0, v[134:135]
	s_add_i32 m0, s52, 0xe000
	s_nop 0
	global_load_lds_dwordx4 v[142:143], off
	s_waitcnt lgkmcnt(8)
	s_barrier
	s_waitcnt lgkmcnt(0)
	s_setprio 1
	v_mfma_f32_16x16x32_bf16 v[120:123], v[160:163], v[192:195], v[120:123]
	v_mfma_f32_16x16x32_bf16 v[124:127], v[168:171], v[192:195], v[124:127]
	v_mfma_f32_16x16x32_bf16 v[108:111], v[160:163], v[200:203], v[108:111]
	v_mfma_f32_16x16x32_bf16 v[104:107], v[168:171], v[200:203], v[104:107]
	v_mfma_f32_16x16x32_bf16 v[92:95], v[160:163], v[208:211], v[92:95]
	v_mfma_f32_16x16x32_bf16 v[88:91], v[168:171], v[208:211], v[88:91]
	v_mfma_f32_16x16x32_bf16 v[76:79], v[160:163], v[216:219], v[76:79]
	v_mfma_f32_16x16x32_bf16 v[72:75], v[168:171], v[216:219], v[72:75]
	v_mfma_f32_16x16x32_bf16 v[120:123], v[164:167], v[196:199], v[120:123]
	v_mfma_f32_16x16x32_bf16 v[124:127], v[188:191], v[196:199], v[124:127]
	v_mfma_f32_16x16x32_bf16 v[108:111], v[164:167], v[204:207], v[108:111]
	v_mfma_f32_16x16x32_bf16 v[104:107], v[188:191], v[204:207], v[104:107]
	v_mfma_f32_16x16x32_bf16 v[92:95], v[164:167], v[212:215], v[92:95]
	v_mfma_f32_16x16x32_bf16 v[88:91], v[188:191], v[212:215], v[88:91]
	v_mfma_f32_16x16x32_bf16 v[76:79], v[164:167], v[220:223], v[76:79]
	v_mfma_f32_16x16x32_bf16 v[72:75], v[188:191], v[220:223], v[72:75]
	s_setprio 0
	s_barrier
	s_add_i32 s29, 0, 0x14000
	v_add_u32_e32 v142, s29, v139
	s_add_i32 s71, s71, s51
	ds_read_b128 v[224:227], v142
	ds_read_b128 v[228:231], v142 offset:1024
	ds_read_b128 v[232:235], v142 offset:2048
	ds_read_b128 v[236:239], v142 offset:3072
	v_lshl_add_u64 v[142:143], s[48:49], 0, v[144:145]
	s_mov_b32 m0, s71
	v_lshl_add_u64 v[240:241], s[48:49], 0, v[128:129]
	global_load_lds_dwordx4 v[142:143], off
	s_add_i32 m0, s71, 0x2000
	s_nop 0
	global_load_lds_dwordx4 v[240:241], off
	s_barrier
	s_waitcnt lgkmcnt(0)
	s_setprio 1
	v_mfma_f32_16x16x32_bf16 v[116:119], v[224:227], v[192:195], v[116:119]
	v_mfma_f32_16x16x32_bf16 v[112:115], v[232:235], v[192:195], v[112:115]
	v_mfma_f32_16x16x32_bf16 v[100:103], v[224:227], v[200:203], v[100:103]
	v_mfma_f32_16x16x32_bf16 v[96:99], v[232:235], v[200:203], v[96:99]
	v_mfma_f32_16x16x32_bf16 v[84:87], v[224:227], v[208:211], v[84:87]
	v_mfma_f32_16x16x32_bf16 v[80:83], v[232:235], v[208:211], v[80:83]
	v_mfma_f32_16x16x32_bf16 v[68:71], v[224:227], v[216:219], v[68:71]
	v_mfma_f32_16x16x32_bf16 v[64:67], v[232:235], v[216:219], v[64:67]
	v_mfma_f32_16x16x32_bf16 v[116:119], v[228:231], v[196:199], v[116:119]
	v_mfma_f32_16x16x32_bf16 v[112:115], v[236:239], v[196:199], v[112:115]
	v_mfma_f32_16x16x32_bf16 v[100:103], v[228:231], v[204:207], v[100:103]
	v_mfma_f32_16x16x32_bf16 v[96:99], v[236:239], v[204:207], v[96:99]
	v_mfma_f32_16x16x32_bf16 v[84:87], v[228:231], v[212:215], v[84:87]
	v_mfma_f32_16x16x32_bf16 v[80:83], v[236:239], v[212:215], v[80:83]
	v_mfma_f32_16x16x32_bf16 v[68:71], v[228:231], v[220:223], v[68:71]
	v_mfma_f32_16x16x32_bf16 v[64:67], v[236:239], v[220:223], v[64:67]
	s_setprio 0
	s_mov_b32 m0, s52
	v_lshl_add_u64 v[242:243], s[8:9], 0, v[132:133]
	s_barrier
	ds_read_b128 v[192:195], v141 offset:16384
	ds_read_b128 v[196:199], v141 offset:17408
	ds_read_b128 v[200:203], v141 offset:18432
	ds_read_b128 v[204:207], v141 offset:19456
	ds_read_b128 v[208:211], v141 offset:20480
	ds_read_b128 v[212:215], v141 offset:21504
	ds_read_b128 v[216:219], v141 offset:22528
	ds_read_b128 v[220:223], v141 offset:23552
	global_load_lds_dwordx4 v[242:243], off
	v_lshl_add_u64 v[244:245], s[8:9], 0, v[130:131]
	s_mov_b32 m0, s53
	s_nop 0
	global_load_lds_dwordx4 v[244:245], off
	s_barrier
	s_waitcnt lgkmcnt(0)
	s_setprio 1
	v_mfma_f32_16x16x32_bf16 v[60:63], v[160:163], v[192:195], v[60:63]
	v_mfma_f32_16x16x32_bf16 v[56:59], v[168:171], v[192:195], v[56:59]
	v_mfma_f32_16x16x32_bf16 v[44:47], v[160:163], v[200:203], v[44:47]
	v_mfma_f32_16x16x32_bf16 v[40:43], v[168:171], v[200:203], v[40:43]
	v_mfma_f32_16x16x32_bf16 v[28:31], v[160:163], v[208:211], v[28:31]
	v_mfma_f32_16x16x32_bf16 v[24:27], v[168:171], v[208:211], v[24:27]
	v_mfma_f32_16x16x32_bf16 v[12:15], v[160:163], v[216:219], v[12:15]
	v_mfma_f32_16x16x32_bf16 v[8:11], v[168:171], v[216:219], v[8:11]
	v_mfma_f32_16x16x32_bf16 v[60:63], v[164:167], v[196:199], v[60:63]
	v_mfma_f32_16x16x32_bf16 v[56:59], v[188:191], v[196:199], v[56:59]
	v_mfma_f32_16x16x32_bf16 v[44:47], v[164:167], v[204:207], v[44:47]
	v_mfma_f32_16x16x32_bf16 v[40:43], v[188:191], v[204:207], v[40:43]
	v_mfma_f32_16x16x32_bf16 v[28:31], v[164:167], v[212:215], v[28:31]
	v_mfma_f32_16x16x32_bf16 v[24:27], v[188:191], v[212:215], v[24:27]
	v_mfma_f32_16x16x32_bf16 v[12:15], v[164:167], v[220:223], v[12:15]
	v_mfma_f32_16x16x32_bf16 v[8:11], v[188:191], v[220:223], v[8:11]
	s_setprio 0
	s_barrier
	s_add_u32 s48, s48, s4
	s_addc_u32 s49, s49, s5
	s_add_i32 s29, s29, s51
	v_lshl_add_u64 v[246:247], s[48:49], 0, v[144:145]
	s_mov_b32 m0, s29
	v_lshl_add_u64 v[248:249], s[48:49], 0, v[128:129]
	global_load_lds_dwordx4 v[246:247], off
	s_add_i32 m0, s29, 0x2000
	s_nop 0
	global_load_lds_dwordx4 v[248:249], off
	s_waitcnt vmcnt(6)
	s_barrier
	s_setprio 1
	v_mfma_f32_16x16x32_bf16 v[52:55], v[224:227], v[192:195], v[52:55]
	v_mfma_f32_16x16x32_bf16 v[48:51], v[232:235], v[192:195], v[48:51]
	v_mfma_f32_16x16x32_bf16 v[36:39], v[224:227], v[200:203], v[36:39]
	v_mfma_f32_16x16x32_bf16 v[32:35], v[232:235], v[200:203], v[32:35]
	v_mfma_f32_16x16x32_bf16 v[20:23], v[224:227], v[208:211], v[20:23]
	v_mfma_f32_16x16x32_bf16 v[16:19], v[232:235], v[208:211], v[16:19]
	v_mfma_f32_16x16x32_bf16 v[4:7], v[224:227], v[216:219], v[4:7]
	v_mfma_f32_16x16x32_bf16 v[0:3], v[232:235], v[216:219], v[0:3]
	v_mfma_f32_16x16x32_bf16 v[52:55], v[228:231], v[196:199], v[52:55]
	v_mfma_f32_16x16x32_bf16 v[48:51], v[236:239], v[196:199], v[48:51]
	v_mfma_f32_16x16x32_bf16 v[36:39], v[228:231], v[204:207], v[36:39]
	v_mfma_f32_16x16x32_bf16 v[32:35], v[236:239], v[204:207], v[32:35]
	v_mfma_f32_16x16x32_bf16 v[20:23], v[228:231], v[212:215], v[20:23]
	v_mfma_f32_16x16x32_bf16 v[16:19], v[236:239], v[212:215], v[16:19]
	v_mfma_f32_16x16x32_bf16 v[4:7], v[228:231], v[220:223], v[4:7]
	v_mfma_f32_16x16x32_bf16 v[0:3], v[236:239], v[220:223], v[0:3]
	s_setprio 0
	s_add_i32 s29, 0, 0x18000
	v_add_u32_e32 v188, s29, v139
	s_barrier
	ds_read_b128 v[160:163], v188
	ds_read_b128 v[164:167], v188 offset:1024
	ds_read_b128 v[168:171], v188 offset:2048
	ds_read_b128 v[188:191], v188 offset:3072
	s_add_u32 s8, s8, s4
	s_addc_u32 s9, s9, s5
	s_mov_b32 m0, s54
	v_lshl_add_u64 v[224:225], s[8:9], 0, v[132:133]
	ds_read_b128 v[192:195], v141 offset:32768
	ds_read_b128 v[196:199], v141 offset:33792
	ds_read_b128 v[200:203], v141 offset:34816
	ds_read_b128 v[204:207], v141 offset:35840
	ds_read_b128 v[208:211], v141 offset:36864
	ds_read_b128 v[212:215], v141 offset:37888
	ds_read_b128 v[216:219], v141 offset:38912
	ds_read_b128 v[220:223], v141 offset:39936
	global_load_lds_dwordx4 v[224:225], off
	v_lshl_add_u64 v[224:225], s[8:9], 0, v[130:131]
	s_mov_b32 m0, s55
	s_nop 0
	global_load_lds_dwordx4 v[224:225], off
	s_waitcnt lgkmcnt(8)
	s_barrier
	s_waitcnt lgkmcnt(0)
	s_setprio 1
	v_mfma_f32_16x16x32_bf16 v[120:123], v[160:163], v[192:195], v[120:123]
	v_mfma_f32_16x16x32_bf16 v[124:127], v[168:171], v[192:195], v[124:127]
	v_mfma_f32_16x16x32_bf16 v[108:111], v[160:163], v[200:203], v[108:111]
	v_mfma_f32_16x16x32_bf16 v[104:107], v[168:171], v[200:203], v[104:107]
	v_mfma_f32_16x16x32_bf16 v[92:95], v[160:163], v[208:211], v[92:95]
	v_mfma_f32_16x16x32_bf16 v[88:91], v[168:171], v[208:211], v[88:91]
	v_mfma_f32_16x16x32_bf16 v[76:79], v[160:163], v[216:219], v[76:79]
	v_mfma_f32_16x16x32_bf16 v[72:75], v[168:171], v[216:219], v[72:75]
	v_mfma_f32_16x16x32_bf16 v[120:123], v[164:167], v[196:199], v[120:123]
	v_mfma_f32_16x16x32_bf16 v[124:127], v[188:191], v[196:199], v[124:127]
	v_mfma_f32_16x16x32_bf16 v[108:111], v[164:167], v[204:207], v[108:111]
	v_mfma_f32_16x16x32_bf16 v[104:107], v[188:191], v[204:207], v[104:107]
	v_mfma_f32_16x16x32_bf16 v[92:95], v[164:167], v[212:215], v[92:95]
	v_mfma_f32_16x16x32_bf16 v[88:91], v[188:191], v[212:215], v[88:91]
	v_mfma_f32_16x16x32_bf16 v[76:79], v[164:167], v[220:223], v[76:79]
	v_mfma_f32_16x16x32_bf16 v[72:75], v[188:191], v[220:223], v[72:75]
	s_setprio 0
	s_barrier
	s_add_i32 s8, 0, 0x1c000
	s_add_i32 s9, s29, s51
	v_add_u32_e32 v236, s8, v139
	v_lshl_add_u64 v[142:143], v[142:143], 0, s[82:83]
	s_mov_b32 m0, s9
	ds_read_b128 v[224:227], v236
	ds_read_b128 v[228:231], v236 offset:1024
	ds_read_b128 v[232:235], v236 offset:2048
	ds_read_b128 v[236:239], v236 offset:3072
	global_load_lds_dwordx4 v[142:143], off
	v_lshl_add_u64 v[142:143], v[240:241], 0, s[82:83]
	s_add_i32 m0, s9, 0x2000
	s_nop 0
	global_load_lds_dwordx4 v[142:143], off
	s_barrier
	s_waitcnt lgkmcnt(0)
	s_setprio 1
	v_mfma_f32_16x16x32_bf16 v[116:119], v[224:227], v[192:195], v[116:119]
	v_mfma_f32_16x16x32_bf16 v[112:115], v[232:235], v[192:195], v[112:115]
	v_mfma_f32_16x16x32_bf16 v[100:103], v[224:227], v[200:203], v[100:103]
	v_mfma_f32_16x16x32_bf16 v[96:99], v[232:235], v[200:203], v[96:99]
	v_mfma_f32_16x16x32_bf16 v[84:87], v[224:227], v[208:211], v[84:87]
	v_mfma_f32_16x16x32_bf16 v[80:83], v[232:235], v[208:211], v[80:83]
	v_mfma_f32_16x16x32_bf16 v[68:71], v[224:227], v[216:219], v[68:71]
	v_mfma_f32_16x16x32_bf16 v[64:67], v[232:235], v[216:219], v[64:67]
	v_mfma_f32_16x16x32_bf16 v[116:119], v[228:231], v[196:199], v[116:119]
	v_mfma_f32_16x16x32_bf16 v[112:115], v[236:239], v[196:199], v[112:115]
	v_mfma_f32_16x16x32_bf16 v[100:103], v[228:231], v[204:207], v[100:103]
	v_mfma_f32_16x16x32_bf16 v[96:99], v[236:239], v[204:207], v[96:99]
	v_mfma_f32_16x16x32_bf16 v[84:87], v[228:231], v[212:215], v[84:87]
	v_mfma_f32_16x16x32_bf16 v[80:83], v[236:239], v[212:215], v[80:83]
	v_mfma_f32_16x16x32_bf16 v[68:71], v[228:231], v[220:223], v[68:71]
	v_mfma_f32_16x16x32_bf16 v[64:67], v[236:239], v[220:223], v[64:67]
	s_setprio 0
	s_mov_b32 m0, s57
	v_lshl_add_u64 v[142:143], v[242:243], 0, s[82:83]
	s_barrier
	ds_read_b128 v[192:195], v141 offset:49152
	ds_read_b128 v[196:199], v141 offset:50176
	ds_read_b128 v[200:203], v141 offset:51200
	ds_read_b128 v[204:207], v141 offset:52224
	ds_read_b128 v[208:211], v141 offset:53248
	ds_read_b128 v[212:215], v141 offset:54272
	ds_read_b128 v[216:219], v141 offset:55296
	ds_read_b128 v[220:223], v141 offset:56320
	global_load_lds_dwordx4 v[142:143], off
	v_lshl_add_u64 v[142:143], v[244:245], 0, s[82:83]
	s_mov_b32 m0, s58
	s_nop 0
	global_load_lds_dwordx4 v[142:143], off
	s_barrier
	s_waitcnt lgkmcnt(0)
	s_setprio 1
	v_mfma_f32_16x16x32_bf16 v[60:63], v[160:163], v[192:195], v[60:63]
	v_mfma_f32_16x16x32_bf16 v[56:59], v[168:171], v[192:195], v[56:59]
	v_mfma_f32_16x16x32_bf16 v[44:47], v[160:163], v[200:203], v[44:47]
	v_mfma_f32_16x16x32_bf16 v[40:43], v[168:171], v[200:203], v[40:43]
	v_mfma_f32_16x16x32_bf16 v[28:31], v[160:163], v[208:211], v[28:31]
	v_mfma_f32_16x16x32_bf16 v[24:27], v[168:171], v[208:211], v[24:27]
	v_mfma_f32_16x16x32_bf16 v[12:15], v[160:163], v[216:219], v[12:15]
	v_mfma_f32_16x16x32_bf16 v[8:11], v[168:171], v[216:219], v[8:11]
	v_mfma_f32_16x16x32_bf16 v[60:63], v[164:167], v[196:199], v[60:63]
	v_mfma_f32_16x16x32_bf16 v[56:59], v[188:191], v[196:199], v[56:59]
	v_mfma_f32_16x16x32_bf16 v[44:47], v[164:167], v[204:207], v[44:47]
	v_mfma_f32_16x16x32_bf16 v[40:43], v[188:191], v[204:207], v[40:43]
	v_mfma_f32_16x16x32_bf16 v[28:31], v[164:167], v[212:215], v[28:31]
	v_mfma_f32_16x16x32_bf16 v[24:27], v[188:191], v[212:215], v[24:27]
	v_mfma_f32_16x16x32_bf16 v[12:15], v[164:167], v[220:223], v[12:15]
	v_mfma_f32_16x16x32_bf16 v[8:11], v[188:191], v[220:223], v[8:11]
	s_setprio 0
	s_barrier
	s_add_i32 s8, s8, s51
	v_lshl_add_u64 v[142:143], v[246:247], 0, s[82:83]
	s_mov_b32 m0, s8
	s_nop 0
	global_load_lds_dwordx4 v[142:143], off
	v_lshl_add_u64 v[142:143], v[248:249], 0, s[82:83]
	s_add_i32 m0, s8, 0x2000
	s_nop 0
	global_load_lds_dwordx4 v[142:143], off
	s_waitcnt vmcnt(6)
	s_barrier
	s_setprio 1
	v_mfma_f32_16x16x32_bf16 v[52:55], v[224:227], v[192:195], v[52:55]
	v_mfma_f32_16x16x32_bf16 v[48:51], v[232:235], v[192:195], v[48:51]
	v_mfma_f32_16x16x32_bf16 v[36:39], v[224:227], v[200:203], v[36:39]
	v_mfma_f32_16x16x32_bf16 v[32:35], v[232:235], v[200:203], v[32:35]
	v_mfma_f32_16x16x32_bf16 v[20:23], v[224:227], v[208:211], v[20:23]
	v_mfma_f32_16x16x32_bf16 v[16:19], v[232:235], v[208:211], v[16:19]
	v_mfma_f32_16x16x32_bf16 v[4:7], v[224:227], v[216:219], v[4:7]
	v_mfma_f32_16x16x32_bf16 v[0:3], v[232:235], v[216:219], v[0:3]
	v_mfma_f32_16x16x32_bf16 v[52:55], v[228:231], v[196:199], v[52:55]
	v_mfma_f32_16x16x32_bf16 v[48:51], v[236:239], v[196:199], v[48:51]
	v_mfma_f32_16x16x32_bf16 v[36:39], v[228:231], v[204:207], v[36:39]
	v_mfma_f32_16x16x32_bf16 v[32:35], v[236:239], v[204:207], v[32:35]
	v_mfma_f32_16x16x32_bf16 v[20:23], v[228:231], v[212:215], v[20:23]
	v_mfma_f32_16x16x32_bf16 v[16:19], v[236:239], v[212:215], v[16:19]
	v_mfma_f32_16x16x32_bf16 v[4:7], v[228:231], v[220:223], v[4:7]
	v_mfma_f32_16x16x32_bf16 v[0:3], v[236:239], v[220:223], v[0:3]
	s_setprio 0
	s_add_u32 s10, s10, 0x100
	s_addc_u32 s11, s11, 0
	s_add_u32 s6, s6, 0x100
	s_addc_u32 s7, s7, 0
	s_cmp_ge_i32 s28, s56
	s_mov_b32 s8, s28
	s_barrier
	s_cbranch_scc0 .LBB0_405
	s_branch .LBB0_392

.LBB0_935:
	s_add_i32 s28, s8, 2
	s_add_u32 s29, s6, 0x80
	s_addc_u32 s9, s7, 0
	s_add_i32 s71, 0, 0x10000
	v_add_u32_e32 v140, s71, v189
	ds_read_b128 v[80:83], v140
	ds_read_b128 v[132:135], v140 offset:1024
	ds_read_b128 v[136:139], v140 offset:2048
	ds_read_b128 v[140:143], v140 offset:3072
	s_cmp_eq_u32 s59, s8
	s_cselect_b32 s8, s44, s29
	s_cselect_b32 s9, s45, s9
	s_cselect_b32 s49, s47, s11
	s_cselect_b32 s48, s46, s10
	v_lshl_add_u64 v[170:171], s[6:7], 0, v[164:165]
	s_add_i32 m0, s52, 0xc000
	ds_read_b128 v[166:169], v191
	ds_read_b128 v[192:195], v191 offset:1024
	ds_read_b128 v[196:199], v191 offset:2048
	ds_read_b128 v[200:203], v191 offset:3072
	ds_read_b128 v[204:207], v191 offset:4096
	ds_read_b128 v[208:211], v191 offset:5120
	ds_read_b128 v[212:215], v191 offset:6144
	ds_read_b128 v[216:219], v191 offset:7168
	global_load_lds_dwordx4 v[170:171], off
	v_lshl_add_u64 v[170:171], s[6:7], 0, v[162:163]
	s_add_i32 m0, s52, 0xe000
	s_nop 0
	global_load_lds_dwordx4 v[170:171], off
	s_waitcnt lgkmcnt(8)
	s_barrier
	s_waitcnt lgkmcnt(0)
	s_setprio 1
	v_mfma_f32_16x16x32_bf16 v[128:131], v[80:83], v[166:169], v[128:131]
	v_mfma_f32_16x16x32_bf16 v[124:127], v[136:139], v[166:169], v[124:127]
	v_mfma_f32_16x16x32_bf16 v[112:115], v[80:83], v[196:199], v[112:115]
	v_mfma_f32_16x16x32_bf16 v[108:111], v[136:139], v[196:199], v[108:111]
	v_mfma_f32_16x16x32_bf16 v[96:99], v[80:83], v[204:207], v[96:99]
	v_mfma_f32_16x16x32_bf16 v[92:95], v[136:139], v[204:207], v[92:95]
	v_mfma_f32_16x16x32_bf16 v[76:79], v[80:83], v[212:215], v[76:79]
	v_mfma_f32_16x16x32_bf16 v[72:75], v[136:139], v[212:215], v[72:75]
	v_mfma_f32_16x16x32_bf16 v[128:131], v[132:135], v[192:195], v[128:131]
	v_mfma_f32_16x16x32_bf16 v[124:127], v[140:143], v[192:195], v[124:127]
	v_mfma_f32_16x16x32_bf16 v[112:115], v[132:135], v[200:203], v[112:115]
	v_mfma_f32_16x16x32_bf16 v[108:111], v[140:143], v[200:203], v[108:111]
	v_mfma_f32_16x16x32_bf16 v[96:99], v[132:135], v[208:211], v[96:99]
	v_mfma_f32_16x16x32_bf16 v[92:95], v[140:143], v[208:211], v[92:95]
	v_mfma_f32_16x16x32_bf16 v[76:79], v[132:135], v[216:219], v[76:79]
	v_mfma_f32_16x16x32_bf16 v[72:75], v[140:143], v[216:219], v[72:75]
	s_setprio 0
	s_barrier
	s_add_i32 s29, 0, 0x14000
	v_add_u32_e32 v170, s29, v189
	s_add_i32 s71, s71, s51
	ds_read_b128 v[220:223], v170
	ds_read_b128 v[224:227], v170 offset:1024
	ds_read_b128 v[228:231], v170 offset:2048
	ds_read_b128 v[232:235], v170 offset:3072
	v_lshl_add_u64 v[170:171], s[48:49], 0, v[144:145]
	s_mov_b32 m0, s71
	v_lshl_add_u64 v[236:237], s[48:49], 0, v[160:161]
	global_load_lds_dwordx4 v[170:171], off
	s_add_i32 m0, s71, 0x2000
	s_nop 0
	global_load_lds_dwordx4 v[236:237], off
	s_barrier
	s_waitcnt lgkmcnt(0)
	s_setprio 1
	v_mfma_f32_16x16x32_bf16 v[120:123], v[220:223], v[166:169], v[120:123]
	v_mfma_f32_16x16x32_bf16 v[116:119], v[228:231], v[166:169], v[116:119]
	v_mfma_f32_16x16x32_bf16 v[104:107], v[220:223], v[196:199], v[104:107]
	v_mfma_f32_16x16x32_bf16 v[100:103], v[228:231], v[196:199], v[100:103]
	v_mfma_f32_16x16x32_bf16 v[88:91], v[220:223], v[204:207], v[88:91]
	v_mfma_f32_16x16x32_bf16 v[84:87], v[228:231], v[204:207], v[84:87]
	v_mfma_f32_16x16x32_bf16 v[68:71], v[220:223], v[212:215], v[68:71]
	v_mfma_f32_16x16x32_bf16 v[64:67], v[228:231], v[212:215], v[64:67]
	v_mfma_f32_16x16x32_bf16 v[120:123], v[224:227], v[192:195], v[120:123]
	v_mfma_f32_16x16x32_bf16 v[116:119], v[232:235], v[192:195], v[116:119]
	v_mfma_f32_16x16x32_bf16 v[104:107], v[224:227], v[200:203], v[104:107]
	v_mfma_f32_16x16x32_bf16 v[100:103], v[232:235], v[200:203], v[100:103]
	v_mfma_f32_16x16x32_bf16 v[88:91], v[224:227], v[208:211], v[88:91]
	v_mfma_f32_16x16x32_bf16 v[84:87], v[232:235], v[208:211], v[84:87]
	v_mfma_f32_16x16x32_bf16 v[68:71], v[224:227], v[216:219], v[68:71]
	v_mfma_f32_16x16x32_bf16 v[64:67], v[232:235], v[216:219], v[64:67]
	s_setprio 0
	s_mov_b32 m0, s52
	v_lshl_add_u64 v[238:239], s[8:9], 0, v[144:145]
	s_barrier
	ds_read_b128 v[166:169], v191 offset:16384
	ds_read_b128 v[192:195], v191 offset:17408
	ds_read_b128 v[196:199], v191 offset:18432
	ds_read_b128 v[200:203], v191 offset:19456
	ds_read_b128 v[204:207], v191 offset:20480
	ds_read_b128 v[208:211], v191 offset:21504
	ds_read_b128 v[212:215], v191 offset:22528
	ds_read_b128 v[216:219], v191 offset:23552
	global_load_lds_dwordx4 v[238:239], off
	v_lshl_add_u64 v[240:241], s[8:9], 0, v[160:161]
	s_mov_b32 m0, s53
	s_nop 0
	global_load_lds_dwordx4 v[240:241], off
	s_barrier
	s_waitcnt lgkmcnt(0)
	s_setprio 1
	v_mfma_f32_16x16x32_bf16 v[60:63], v[80:83], v[166:169], v[60:63]
	v_mfma_f32_16x16x32_bf16 v[56:59], v[136:139], v[166:169], v[56:59]
	v_mfma_f32_16x16x32_bf16 v[44:47], v[80:83], v[196:199], v[44:47]
	v_mfma_f32_16x16x32_bf16 v[40:43], v[136:139], v[196:199], v[40:43]
	v_mfma_f32_16x16x32_bf16 v[28:31], v[80:83], v[204:207], v[28:31]
	v_mfma_f32_16x16x32_bf16 v[24:27], v[136:139], v[204:207], v[24:27]
	v_mfma_f32_16x16x32_bf16 v[12:15], v[80:83], v[212:215], v[12:15]
	v_mfma_f32_16x16x32_bf16 v[8:11], v[136:139], v[212:215], v[8:11]
	v_mfma_f32_16x16x32_bf16 v[60:63], v[132:135], v[192:195], v[60:63]
	v_mfma_f32_16x16x32_bf16 v[56:59], v[140:143], v[192:195], v[56:59]
	v_mfma_f32_16x16x32_bf16 v[44:47], v[132:135], v[200:203], v[44:47]
	v_mfma_f32_16x16x32_bf16 v[40:43], v[140:143], v[200:203], v[40:43]
	v_mfma_f32_16x16x32_bf16 v[28:31], v[132:135], v[208:211], v[28:31]
	v_mfma_f32_16x16x32_bf16 v[24:27], v[140:143], v[208:211], v[24:27]
	v_mfma_f32_16x16x32_bf16 v[12:15], v[132:135], v[216:219], v[12:15]
	v_mfma_f32_16x16x32_bf16 v[8:11], v[140:143], v[216:219], v[8:11]
	s_setprio 0
	s_barrier
	s_add_u32 s48, s48, s4
	s_addc_u32 s49, s49, s5
	s_add_i32 s29, s29, s51
	v_lshl_add_u64 v[242:243], s[48:49], 0, v[144:145]
	s_mov_b32 m0, s29
	v_lshl_add_u64 v[244:245], s[48:49], 0, v[160:161]
	global_load_lds_dwordx4 v[242:243], off
	s_add_i32 m0, s29, 0x2000
	s_nop 0
	global_load_lds_dwordx4 v[244:245], off
	s_waitcnt vmcnt(6)
	s_barrier
	s_setprio 1
	v_mfma_f32_16x16x32_bf16 v[52:55], v[220:223], v[166:169], v[52:55]
	v_mfma_f32_16x16x32_bf16 v[48:51], v[228:231], v[166:169], v[48:51]
	v_mfma_f32_16x16x32_bf16 v[36:39], v[220:223], v[196:199], v[36:39]
	v_mfma_f32_16x16x32_bf16 v[32:35], v[228:231], v[196:199], v[32:35]
	v_mfma_f32_16x16x32_bf16 v[20:23], v[220:223], v[204:207], v[20:23]
	v_mfma_f32_16x16x32_bf16 v[16:19], v[228:231], v[204:207], v[16:19]
	v_mfma_f32_16x16x32_bf16 v[4:7], v[220:223], v[212:215], v[4:7]
	v_mfma_f32_16x16x32_bf16 v[0:3], v[228:231], v[212:215], v[0:3]
	v_mfma_f32_16x16x32_bf16 v[52:55], v[224:227], v[192:195], v[52:55]
	v_mfma_f32_16x16x32_bf16 v[48:51], v[232:235], v[192:195], v[48:51]
	v_mfma_f32_16x16x32_bf16 v[36:39], v[224:227], v[200:203], v[36:39]
	v_mfma_f32_16x16x32_bf16 v[32:35], v[232:235], v[200:203], v[32:35]
	v_mfma_f32_16x16x32_bf16 v[20:23], v[224:227], v[208:211], v[20:23]
	v_mfma_f32_16x16x32_bf16 v[16:19], v[232:235], v[208:211], v[16:19]
	v_mfma_f32_16x16x32_bf16 v[4:7], v[224:227], v[216:219], v[4:7]
	v_mfma_f32_16x16x32_bf16 v[0:3], v[232:235], v[216:219], v[0:3]
	s_setprio 0
	s_add_i32 s29, 0, 0x18000
	v_add_u32_e32 v140, s29, v189
	s_barrier
	ds_read_b128 v[80:83], v140
	ds_read_b128 v[132:135], v140 offset:1024
	ds_read_b128 v[136:139], v140 offset:2048
	ds_read_b128 v[140:143], v140 offset:3072
	s_add_u32 s8, s8, s4
	s_addc_u32 s9, s9, s5
	s_mov_b32 m0, s54
	v_lshl_add_u64 v[220:221], s[8:9], 0, v[144:145]
	ds_read_b128 v[166:169], v191 offset:32768
	ds_read_b128 v[192:195], v191 offset:33792
	ds_read_b128 v[196:199], v191 offset:34816
	ds_read_b128 v[200:203], v191 offset:35840
	ds_read_b128 v[204:207], v191 offset:36864
	ds_read_b128 v[208:211], v191 offset:37888
	ds_read_b128 v[212:215], v191 offset:38912
	ds_read_b128 v[216:219], v191 offset:39936
	global_load_lds_dwordx4 v[220:221], off
	v_lshl_add_u64 v[220:221], s[8:9], 0, v[160:161]
	s_mov_b32 m0, s55
	s_nop 0
	global_load_lds_dwordx4 v[220:221], off
	s_waitcnt lgkmcnt(8)
	s_barrier
	s_waitcnt lgkmcnt(0)
	s_setprio 1
	v_mfma_f32_16x16x32_bf16 v[128:131], v[80:83], v[166:169], v[128:131]
	v_mfma_f32_16x16x32_bf16 v[124:127], v[136:139], v[166:169], v[124:127]
	v_mfma_f32_16x16x32_bf16 v[112:115], v[80:83], v[196:199], v[112:115]
	v_mfma_f32_16x16x32_bf16 v[108:111], v[136:139], v[196:199], v[108:111]
	v_mfma_f32_16x16x32_bf16 v[96:99], v[80:83], v[204:207], v[96:99]
	v_mfma_f32_16x16x32_bf16 v[92:95], v[136:139], v[204:207], v[92:95]
	v_mfma_f32_16x16x32_bf16 v[76:79], v[80:83], v[212:215], v[76:79]
	v_mfma_f32_16x16x32_bf16 v[72:75], v[136:139], v[212:215], v[72:75]
	v_mfma_f32_16x16x32_bf16 v[128:131], v[132:135], v[192:195], v[128:131]
	v_mfma_f32_16x16x32_bf16 v[124:127], v[140:143], v[192:195], v[124:127]
	v_mfma_f32_16x16x32_bf16 v[112:115], v[132:135], v[200:203], v[112:115]
	v_mfma_f32_16x16x32_bf16 v[108:111], v[140:143], v[200:203], v[108:111]
	v_mfma_f32_16x16x32_bf16 v[96:99], v[132:135], v[208:211], v[96:99]
	v_mfma_f32_16x16x32_bf16 v[92:95], v[140:143], v[208:211], v[92:95]
	v_mfma_f32_16x16x32_bf16 v[76:79], v[132:135], v[216:219], v[76:79]
	v_mfma_f32_16x16x32_bf16 v[72:75], v[140:143], v[216:219], v[72:75]
	s_setprio 0
	s_barrier
	s_add_i32 s8, 0, 0x1c000
	s_add_i32 s9, s29, s51
	v_add_u32_e32 v232, s8, v189
	v_lshl_add_u64 v[170:171], v[170:171], 0, s[82:83]
	s_mov_b32 m0, s9
	ds_read_b128 v[220:223], v232
	ds_read_b128 v[224:227], v232 offset:1024
	ds_read_b128 v[228:231], v232 offset:2048
	ds_read_b128 v[232:235], v232 offset:3072
	global_load_lds_dwordx4 v[170:171], off
	v_lshl_add_u64 v[170:171], v[236:237], 0, s[82:83]
	s_add_i32 m0, s9, 0x2000
	s_nop 0
	global_load_lds_dwordx4 v[170:171], off
	s_barrier
	s_waitcnt lgkmcnt(0)
	s_setprio 1
	v_mfma_f32_16x16x32_bf16 v[120:123], v[220:223], v[166:169], v[120:123]
	v_mfma_f32_16x16x32_bf16 v[116:119], v[228:231], v[166:169], v[116:119]
	v_mfma_f32_16x16x32_bf16 v[104:107], v[220:223], v[196:199], v[104:107]
	v_mfma_f32_16x16x32_bf16 v[100:103], v[228:231], v[196:199], v[100:103]
	v_mfma_f32_16x16x32_bf16 v[88:91], v[220:223], v[204:207], v[88:91]
	v_mfma_f32_16x16x32_bf16 v[84:87], v[228:231], v[204:207], v[84:87]
	v_mfma_f32_16x16x32_bf16 v[68:71], v[220:223], v[212:215], v[68:71]
	v_mfma_f32_16x16x32_bf16 v[64:67], v[228:231], v[212:215], v[64:67]
	v_mfma_f32_16x16x32_bf16 v[120:123], v[224:227], v[192:195], v[120:123]
	v_mfma_f32_16x16x32_bf16 v[116:119], v[232:235], v[192:195], v[116:119]
	v_mfma_f32_16x16x32_bf16 v[104:107], v[224:227], v[200:203], v[104:107]
	v_mfma_f32_16x16x32_bf16 v[100:103], v[232:235], v[200:203], v[100:103]
	v_mfma_f32_16x16x32_bf16 v[88:91], v[224:227], v[208:211], v[88:91]
	v_mfma_f32_16x16x32_bf16 v[84:87], v[232:235], v[208:211], v[84:87]
	v_mfma_f32_16x16x32_bf16 v[68:71], v[224:227], v[216:219], v[68:71]
	v_mfma_f32_16x16x32_bf16 v[64:67], v[232:235], v[216:219], v[64:67]
	s_setprio 0
	s_mov_b32 m0, s57
	v_lshl_add_u64 v[170:171], v[238:239], 0, s[82:83]
	s_barrier
	ds_read_b128 v[166:169], v191 offset:49152
	ds_read_b128 v[192:195], v191 offset:50176
	ds_read_b128 v[196:199], v191 offset:51200
	ds_read_b128 v[200:203], v191 offset:52224
	ds_read_b128 v[204:207], v191 offset:53248
	ds_read_b128 v[208:211], v191 offset:54272
	ds_read_b128 v[212:215], v191 offset:55296
	ds_read_b128 v[216:219], v191 offset:56320
	global_load_lds_dwordx4 v[170:171], off
	v_lshl_add_u64 v[170:171], v[240:241], 0, s[82:83]
	s_mov_b32 m0, s58
	s_nop 0
	global_load_lds_dwordx4 v[170:171], off
	s_barrier
	s_waitcnt lgkmcnt(0)
	s_setprio 1
	v_mfma_f32_16x16x32_bf16 v[60:63], v[80:83], v[166:169], v[60:63]
	v_mfma_f32_16x16x32_bf16 v[56:59], v[136:139], v[166:169], v[56:59]
	v_mfma_f32_16x16x32_bf16 v[44:47], v[80:83], v[196:199], v[44:47]
	v_mfma_f32_16x16x32_bf16 v[40:43], v[136:139], v[196:199], v[40:43]
	v_mfma_f32_16x16x32_bf16 v[28:31], v[80:83], v[204:207], v[28:31]
	v_mfma_f32_16x16x32_bf16 v[24:27], v[136:139], v[204:207], v[24:27]
	v_mfma_f32_16x16x32_bf16 v[12:15], v[80:83], v[212:215], v[12:15]
	v_mfma_f32_16x16x32_bf16 v[8:11], v[136:139], v[212:215], v[8:11]
	v_mfma_f32_16x16x32_bf16 v[60:63], v[132:135], v[192:195], v[60:63]
	v_mfma_f32_16x16x32_bf16 v[56:59], v[140:143], v[192:195], v[56:59]
	v_mfma_f32_16x16x32_bf16 v[44:47], v[132:135], v[200:203], v[44:47]
	v_mfma_f32_16x16x32_bf16 v[40:43], v[140:143], v[200:203], v[40:43]
	v_mfma_f32_16x16x32_bf16 v[28:31], v[132:135], v[208:211], v[28:31]
	v_mfma_f32_16x16x32_bf16 v[24:27], v[140:143], v[208:211], v[24:27]
	v_mfma_f32_16x16x32_bf16 v[12:15], v[132:135], v[216:219], v[12:15]
	v_mfma_f32_16x16x32_bf16 v[8:11], v[140:143], v[216:219], v[8:11]
	s_setprio 0
	s_barrier
	s_add_i32 s8, s8, s51
	v_lshl_add_u64 v[80:81], v[242:243], 0, s[82:83]
	s_mov_b32 m0, s8
	s_nop 0
	global_load_lds_dwordx4 v[80:81], off
	v_lshl_add_u64 v[80:81], v[244:245], 0, s[82:83]
	s_add_i32 m0, s8, 0x2000
	s_nop 0
	global_load_lds_dwordx4 v[80:81], off
	s_waitcnt vmcnt(6)
	s_barrier
	s_setprio 1
	v_mfma_f32_16x16x32_bf16 v[52:55], v[220:223], v[166:169], v[52:55]
	v_mfma_f32_16x16x32_bf16 v[48:51], v[228:231], v[166:169], v[48:51]
	v_mfma_f32_16x16x32_bf16 v[36:39], v[220:223], v[196:199], v[36:39]
	v_mfma_f32_16x16x32_bf16 v[32:35], v[228:231], v[196:199], v[32:35]
	v_mfma_f32_16x16x32_bf16 v[20:23], v[220:223], v[204:207], v[20:23]
	v_mfma_f32_16x16x32_bf16 v[16:19], v[228:231], v[204:207], v[16:19]
	v_mfma_f32_16x16x32_bf16 v[4:7], v[220:223], v[212:215], v[4:7]
	v_mfma_f32_16x16x32_bf16 v[0:3], v[228:231], v[212:215], v[0:3]
	v_mfma_f32_16x16x32_bf16 v[52:55], v[224:227], v[192:195], v[52:55]
	v_mfma_f32_16x16x32_bf16 v[48:51], v[232:235], v[192:195], v[48:51]
	v_mfma_f32_16x16x32_bf16 v[36:39], v[224:227], v[200:203], v[36:39]
	v_mfma_f32_16x16x32_bf16 v[32:35], v[232:235], v[200:203], v[32:35]
	v_mfma_f32_16x16x32_bf16 v[20:23], v[224:227], v[208:211], v[20:23]
	v_mfma_f32_16x16x32_bf16 v[16:19], v[232:235], v[208:211], v[16:19]
	v_mfma_f32_16x16x32_bf16 v[4:7], v[224:227], v[216:219], v[4:7]
	v_mfma_f32_16x16x32_bf16 v[0:3], v[232:235], v[216:219], v[0:3]
	s_setprio 0
	s_add_u32 s10, s10, 0x100
	s_addc_u32 s11, s11, 0
	s_add_u32 s6, s6, 0x100
	s_addc_u32 s7, s7, 0
	s_cmp_ge_i32 s28, s56
	s_mov_b32 s8, s28
	s_barrier
	s_cbranch_scc0 .LBB0_935
	s_branch .LBB0_922

.LBB0_1059:
	s_add_i32 s28, s8, 2
	s_add_u32 s29, s6, 0x80
	s_addc_u32 s9, s7, 0
	s_add_i32 s71, 0, 0x10000
	v_add_u32_e32 v138, s71, v141
	ds_read_b128 v[160:163], v138
	ds_read_b128 v[164:167], v138 offset:1024
	ds_read_b128 v[168:171], v138 offset:2048
	ds_read_b128 v[188:191], v138 offset:3072
	s_cmp_eq_u32 s59, s8
	s_cselect_b32 s8, s42, s29
	s_cselect_b32 s9, s43, s9
	s_cselect_b32 s49, s45, s11
	s_cselect_b32 s48, s44, s10
	v_lshl_add_u64 v[138:139], s[6:7], 0, v[136:137]
	s_add_i32 m0, s52, 0xc000
	ds_read_b128 v[192:195], v143
	ds_read_b128 v[196:199], v143 offset:1024
	ds_read_b128 v[200:203], v143 offset:2048
	ds_read_b128 v[204:207], v143 offset:3072
	ds_read_b128 v[208:211], v143 offset:4096
	ds_read_b128 v[212:215], v143 offset:5120
	ds_read_b128 v[216:219], v143 offset:6144
	ds_read_b128 v[220:223], v143 offset:7168
	global_load_lds_dwordx4 v[138:139], off
	v_lshl_add_u64 v[138:139], s[6:7], 0, v[134:135]
	s_add_i32 m0, s52, 0xe000
	s_nop 0
	global_load_lds_dwordx4 v[138:139], off
	s_waitcnt lgkmcnt(8)
	s_barrier
	s_waitcnt lgkmcnt(0)
	s_setprio 1
	v_mfma_f32_16x16x32_bf16 v[120:123], v[160:163], v[192:195], v[120:123]
	v_mfma_f32_16x16x32_bf16 v[112:115], v[168:171], v[192:195], v[112:115]
	v_mfma_f32_16x16x32_bf16 v[104:107], v[160:163], v[200:203], v[104:107]
	v_mfma_f32_16x16x32_bf16 v[96:99], v[168:171], v[200:203], v[96:99]
	v_mfma_f32_16x16x32_bf16 v[88:91], v[160:163], v[208:211], v[88:91]
	v_mfma_f32_16x16x32_bf16 v[80:83], v[168:171], v[208:211], v[80:83]
	v_mfma_f32_16x16x32_bf16 v[72:75], v[160:163], v[216:219], v[72:75]
	v_mfma_f32_16x16x32_bf16 v[64:67], v[168:171], v[216:219], v[64:67]
	v_mfma_f32_16x16x32_bf16 v[120:123], v[164:167], v[196:199], v[120:123]
	v_mfma_f32_16x16x32_bf16 v[112:115], v[188:191], v[196:199], v[112:115]
	v_mfma_f32_16x16x32_bf16 v[104:107], v[164:167], v[204:207], v[104:107]
	v_mfma_f32_16x16x32_bf16 v[96:99], v[188:191], v[204:207], v[96:99]
	v_mfma_f32_16x16x32_bf16 v[88:91], v[164:167], v[212:215], v[88:91]
	v_mfma_f32_16x16x32_bf16 v[80:83], v[188:191], v[212:215], v[80:83]
	v_mfma_f32_16x16x32_bf16 v[72:75], v[164:167], v[220:223], v[72:75]
	v_mfma_f32_16x16x32_bf16 v[64:67], v[188:191], v[220:223], v[64:67]
	s_setprio 0
	s_barrier
	s_add_i32 s29, 0, 0x14000
	v_add_u32_e32 v138, s29, v141
	s_add_i32 s71, s71, s51
	ds_read_b128 v[224:227], v138
	ds_read_b128 v[228:231], v138 offset:1024
	ds_read_b128 v[232:235], v138 offset:2048
	ds_read_b128 v[236:239], v138 offset:3072
	v_lshl_add_u64 v[138:139], s[48:49], 0, v[144:145]
	s_mov_b32 m0, s71
	v_lshl_add_u64 v[240:241], s[48:49], 0, v[128:129]
	global_load_lds_dwordx4 v[138:139], off
	s_add_i32 m0, s71, 0x2000
	s_nop 0
	global_load_lds_dwordx4 v[240:241], off
	s_barrier
	s_waitcnt lgkmcnt(0)
	s_setprio 1
	v_mfma_f32_16x16x32_bf16 v[124:127], v[224:227], v[192:195], v[124:127]
	v_mfma_f32_16x16x32_bf16 v[116:119], v[232:235], v[192:195], v[116:119]
	v_mfma_f32_16x16x32_bf16 v[108:111], v[224:227], v[200:203], v[108:111]
	v_mfma_f32_16x16x32_bf16 v[100:103], v[232:235], v[200:203], v[100:103]
	v_mfma_f32_16x16x32_bf16 v[92:95], v[224:227], v[208:211], v[92:95]
	v_mfma_f32_16x16x32_bf16 v[84:87], v[232:235], v[208:211], v[84:87]
	v_mfma_f32_16x16x32_bf16 v[76:79], v[224:227], v[216:219], v[76:79]
	v_mfma_f32_16x16x32_bf16 v[68:71], v[232:235], v[216:219], v[68:71]
	v_mfma_f32_16x16x32_bf16 v[124:127], v[228:231], v[196:199], v[124:127]
	v_mfma_f32_16x16x32_bf16 v[116:119], v[236:239], v[196:199], v[116:119]
	v_mfma_f32_16x16x32_bf16 v[108:111], v[228:231], v[204:207], v[108:111]
	v_mfma_f32_16x16x32_bf16 v[100:103], v[236:239], v[204:207], v[100:103]
	v_mfma_f32_16x16x32_bf16 v[92:95], v[228:231], v[212:215], v[92:95]
	v_mfma_f32_16x16x32_bf16 v[84:87], v[236:239], v[212:215], v[84:87]
	v_mfma_f32_16x16x32_bf16 v[76:79], v[228:231], v[220:223], v[76:79]
	v_mfma_f32_16x16x32_bf16 v[68:71], v[236:239], v[220:223], v[68:71]
	s_setprio 0
	s_mov_b32 m0, s52
	v_lshl_add_u64 v[242:243], s[8:9], 0, v[132:133]
	s_barrier
	ds_read_b128 v[192:195], v143 offset:16384
	ds_read_b128 v[196:199], v143 offset:17408
	ds_read_b128 v[200:203], v143 offset:18432
	ds_read_b128 v[204:207], v143 offset:19456
	ds_read_b128 v[208:211], v143 offset:20480
	ds_read_b128 v[212:215], v143 offset:21504
	ds_read_b128 v[216:219], v143 offset:22528
	ds_read_b128 v[220:223], v143 offset:23552
	global_load_lds_dwordx4 v[242:243], off
	v_lshl_add_u64 v[244:245], s[8:9], 0, v[130:131]
	s_mov_b32 m0, s53
	s_nop 0
	global_load_lds_dwordx4 v[244:245], off
	s_barrier
	s_waitcnt lgkmcnt(0)
	s_setprio 1
	v_mfma_f32_16x16x32_bf16 v[56:59], v[160:163], v[192:195], v[56:59]
	v_mfma_f32_16x16x32_bf16 v[48:51], v[168:171], v[192:195], v[48:51]
	v_mfma_f32_16x16x32_bf16 v[40:43], v[160:163], v[200:203], v[40:43]
	v_mfma_f32_16x16x32_bf16 v[32:35], v[168:171], v[200:203], v[32:35]
	v_mfma_f32_16x16x32_bf16 v[24:27], v[160:163], v[208:211], v[24:27]
	v_mfma_f32_16x16x32_bf16 v[16:19], v[168:171], v[208:211], v[16:19]
	v_mfma_f32_16x16x32_bf16 v[8:11], v[160:163], v[216:219], v[8:11]
	v_mfma_f32_16x16x32_bf16 v[0:3], v[168:171], v[216:219], v[0:3]
	v_mfma_f32_16x16x32_bf16 v[56:59], v[164:167], v[196:199], v[56:59]
	v_mfma_f32_16x16x32_bf16 v[48:51], v[188:191], v[196:199], v[48:51]
	v_mfma_f32_16x16x32_bf16 v[40:43], v[164:167], v[204:207], v[40:43]
	v_mfma_f32_16x16x32_bf16 v[32:35], v[188:191], v[204:207], v[32:35]
	v_mfma_f32_16x16x32_bf16 v[24:27], v[164:167], v[212:215], v[24:27]
	v_mfma_f32_16x16x32_bf16 v[16:19], v[188:191], v[212:215], v[16:19]
	v_mfma_f32_16x16x32_bf16 v[8:11], v[164:167], v[220:223], v[8:11]
	v_mfma_f32_16x16x32_bf16 v[0:3], v[188:191], v[220:223], v[0:3]
	s_setprio 0
	s_barrier
	s_add_u32 s48, s48, s4
	s_addc_u32 s49, s49, s5
	s_add_i32 s29, s29, s51
	v_lshl_add_u64 v[246:247], s[48:49], 0, v[144:145]
	s_mov_b32 m0, s29
	v_lshl_add_u64 v[248:249], s[48:49], 0, v[128:129]
	global_load_lds_dwordx4 v[246:247], off
	s_add_i32 m0, s29, 0x2000
	s_nop 0
	global_load_lds_dwordx4 v[248:249], off
	s_waitcnt vmcnt(6)
	s_barrier
	s_setprio 1
	v_mfma_f32_16x16x32_bf16 v[60:63], v[224:227], v[192:195], v[60:63]
	v_mfma_f32_16x16x32_bf16 v[52:55], v[232:235], v[192:195], v[52:55]
	v_mfma_f32_16x16x32_bf16 v[44:47], v[224:227], v[200:203], v[44:47]
	v_mfma_f32_16x16x32_bf16 v[36:39], v[232:235], v[200:203], v[36:39]
	v_mfma_f32_16x16x32_bf16 v[28:31], v[224:227], v[208:211], v[28:31]
	v_mfma_f32_16x16x32_bf16 v[20:23], v[232:235], v[208:211], v[20:23]
	v_mfma_f32_16x16x32_bf16 v[12:15], v[224:227], v[216:219], v[12:15]
	v_mfma_f32_16x16x32_bf16 v[4:7], v[232:235], v[216:219], v[4:7]
	v_mfma_f32_16x16x32_bf16 v[60:63], v[228:231], v[196:199], v[60:63]
	v_mfma_f32_16x16x32_bf16 v[52:55], v[236:239], v[196:199], v[52:55]
	v_mfma_f32_16x16x32_bf16 v[44:47], v[228:231], v[204:207], v[44:47]
	v_mfma_f32_16x16x32_bf16 v[36:39], v[236:239], v[204:207], v[36:39]
	v_mfma_f32_16x16x32_bf16 v[28:31], v[228:231], v[212:215], v[28:31]
	v_mfma_f32_16x16x32_bf16 v[20:23], v[236:239], v[212:215], v[20:23]
	v_mfma_f32_16x16x32_bf16 v[12:15], v[228:231], v[220:223], v[12:15]
	v_mfma_f32_16x16x32_bf16 v[4:7], v[236:239], v[220:223], v[4:7]
	s_setprio 0
	s_add_i32 s29, 0, 0x18000
	v_add_u32_e32 v188, s29, v141
	s_barrier
	ds_read_b128 v[160:163], v188
	ds_read_b128 v[164:167], v188 offset:1024
	ds_read_b128 v[168:171], v188 offset:2048
	ds_read_b128 v[188:191], v188 offset:3072
	s_add_u32 s8, s8, s4
	s_addc_u32 s9, s9, s5
	s_mov_b32 m0, s54
	v_lshl_add_u64 v[224:225], s[8:9], 0, v[132:133]
	ds_read_b128 v[192:195], v143 offset:32768
	ds_read_b128 v[196:199], v143 offset:33792
	ds_read_b128 v[200:203], v143 offset:34816
	ds_read_b128 v[204:207], v143 offset:35840
	ds_read_b128 v[208:211], v143 offset:36864
	ds_read_b128 v[212:215], v143 offset:37888
	ds_read_b128 v[216:219], v143 offset:38912
	ds_read_b128 v[220:223], v143 offset:39936
	global_load_lds_dwordx4 v[224:225], off
	v_lshl_add_u64 v[224:225], s[8:9], 0, v[130:131]
	s_mov_b32 m0, s55
	s_nop 0
	global_load_lds_dwordx4 v[224:225], off
	s_waitcnt lgkmcnt(8)
	s_barrier
	s_waitcnt lgkmcnt(0)
	s_setprio 1
	v_mfma_f32_16x16x32_bf16 v[120:123], v[160:163], v[192:195], v[120:123]
	v_mfma_f32_16x16x32_bf16 v[112:115], v[168:171], v[192:195], v[112:115]
	v_mfma_f32_16x16x32_bf16 v[104:107], v[160:163], v[200:203], v[104:107]
	v_mfma_f32_16x16x32_bf16 v[96:99], v[168:171], v[200:203], v[96:99]
	v_mfma_f32_16x16x32_bf16 v[88:91], v[160:163], v[208:211], v[88:91]
	v_mfma_f32_16x16x32_bf16 v[80:83], v[168:171], v[208:211], v[80:83]
	v_mfma_f32_16x16x32_bf16 v[72:75], v[160:163], v[216:219], v[72:75]
	v_mfma_f32_16x16x32_bf16 v[64:67], v[168:171], v[216:219], v[64:67]
	v_mfma_f32_16x16x32_bf16 v[120:123], v[164:167], v[196:199], v[120:123]
	v_mfma_f32_16x16x32_bf16 v[112:115], v[188:191], v[196:199], v[112:115]
	v_mfma_f32_16x16x32_bf16 v[104:107], v[164:167], v[204:207], v[104:107]
	v_mfma_f32_16x16x32_bf16 v[96:99], v[188:191], v[204:207], v[96:99]
	v_mfma_f32_16x16x32_bf16 v[88:91], v[164:167], v[212:215], v[88:91]
	v_mfma_f32_16x16x32_bf16 v[80:83], v[188:191], v[212:215], v[80:83]
	v_mfma_f32_16x16x32_bf16 v[72:75], v[164:167], v[220:223], v[72:75]
	v_mfma_f32_16x16x32_bf16 v[64:67], v[188:191], v[220:223], v[64:67]
	s_setprio 0
	s_barrier
	s_add_i32 s8, 0, 0x1c000
	s_add_i32 s9, s29, s51
	v_add_u32_e32 v236, s8, v141
	v_lshl_add_u64 v[138:139], v[138:139], 0, s[82:83]
	s_mov_b32 m0, s9
	ds_read_b128 v[224:227], v236
	ds_read_b128 v[228:231], v236 offset:1024
	ds_read_b128 v[232:235], v236 offset:2048
	ds_read_b128 v[236:239], v236 offset:3072
	global_load_lds_dwordx4 v[138:139], off
	v_lshl_add_u64 v[138:139], v[240:241], 0, s[82:83]
	s_add_i32 m0, s9, 0x2000
	s_nop 0
	global_load_lds_dwordx4 v[138:139], off
	s_barrier
	s_waitcnt lgkmcnt(0)
	s_setprio 1
	v_mfma_f32_16x16x32_bf16 v[124:127], v[224:227], v[192:195], v[124:127]
	v_mfma_f32_16x16x32_bf16 v[116:119], v[232:235], v[192:195], v[116:119]
	v_mfma_f32_16x16x32_bf16 v[108:111], v[224:227], v[200:203], v[108:111]
	v_mfma_f32_16x16x32_bf16 v[100:103], v[232:235], v[200:203], v[100:103]
	v_mfma_f32_16x16x32_bf16 v[92:95], v[224:227], v[208:211], v[92:95]
	v_mfma_f32_16x16x32_bf16 v[84:87], v[232:235], v[208:211], v[84:87]
	v_mfma_f32_16x16x32_bf16 v[76:79], v[224:227], v[216:219], v[76:79]
	v_mfma_f32_16x16x32_bf16 v[68:71], v[232:235], v[216:219], v[68:71]
	v_mfma_f32_16x16x32_bf16 v[124:127], v[228:231], v[196:199], v[124:127]
	v_mfma_f32_16x16x32_bf16 v[116:119], v[236:239], v[196:199], v[116:119]
	v_mfma_f32_16x16x32_bf16 v[108:111], v[228:231], v[204:207], v[108:111]
	v_mfma_f32_16x16x32_bf16 v[100:103], v[236:239], v[204:207], v[100:103]
	v_mfma_f32_16x16x32_bf16 v[92:95], v[228:231], v[212:215], v[92:95]
	v_mfma_f32_16x16x32_bf16 v[84:87], v[236:239], v[212:215], v[84:87]
	v_mfma_f32_16x16x32_bf16 v[76:79], v[228:231], v[220:223], v[76:79]
	v_mfma_f32_16x16x32_bf16 v[68:71], v[236:239], v[220:223], v[68:71]
	s_setprio 0
	s_mov_b32 m0, s57
	v_lshl_add_u64 v[138:139], v[242:243], 0, s[82:83]
	s_barrier
	ds_read_b128 v[192:195], v143 offset:49152
	ds_read_b128 v[196:199], v143 offset:50176
	ds_read_b128 v[200:203], v143 offset:51200
	ds_read_b128 v[204:207], v143 offset:52224
	ds_read_b128 v[208:211], v143 offset:53248
	ds_read_b128 v[212:215], v143 offset:54272
	ds_read_b128 v[216:219], v143 offset:55296
	ds_read_b128 v[220:223], v143 offset:56320
	global_load_lds_dwordx4 v[138:139], off
	v_lshl_add_u64 v[138:139], v[244:245], 0, s[82:83]
	s_mov_b32 m0, s58
	s_nop 0
	global_load_lds_dwordx4 v[138:139], off
	s_barrier
	s_waitcnt lgkmcnt(0)
	s_setprio 1
	v_mfma_f32_16x16x32_bf16 v[56:59], v[160:163], v[192:195], v[56:59]
	v_mfma_f32_16x16x32_bf16 v[48:51], v[168:171], v[192:195], v[48:51]
	v_mfma_f32_16x16x32_bf16 v[40:43], v[160:163], v[200:203], v[40:43]
	v_mfma_f32_16x16x32_bf16 v[32:35], v[168:171], v[200:203], v[32:35]
	v_mfma_f32_16x16x32_bf16 v[24:27], v[160:163], v[208:211], v[24:27]
	v_mfma_f32_16x16x32_bf16 v[16:19], v[168:171], v[208:211], v[16:19]
	v_mfma_f32_16x16x32_bf16 v[8:11], v[160:163], v[216:219], v[8:11]
	v_mfma_f32_16x16x32_bf16 v[0:3], v[168:171], v[216:219], v[0:3]
	v_mfma_f32_16x16x32_bf16 v[56:59], v[164:167], v[196:199], v[56:59]
	v_mfma_f32_16x16x32_bf16 v[48:51], v[188:191], v[196:199], v[48:51]
	v_mfma_f32_16x16x32_bf16 v[40:43], v[164:167], v[204:207], v[40:43]
	v_mfma_f32_16x16x32_bf16 v[32:35], v[188:191], v[204:207], v[32:35]
	v_mfma_f32_16x16x32_bf16 v[24:27], v[164:167], v[212:215], v[24:27]
	v_mfma_f32_16x16x32_bf16 v[16:19], v[188:191], v[212:215], v[16:19]
	v_mfma_f32_16x16x32_bf16 v[8:11], v[164:167], v[220:223], v[8:11]
	v_mfma_f32_16x16x32_bf16 v[0:3], v[188:191], v[220:223], v[0:3]
	s_setprio 0
	s_barrier
	s_add_i32 s8, s8, s51
	v_lshl_add_u64 v[138:139], v[246:247], 0, s[82:83]
	s_mov_b32 m0, s8
	s_nop 0
	global_load_lds_dwordx4 v[138:139], off
	v_lshl_add_u64 v[138:139], v[248:249], 0, s[82:83]
	s_add_i32 m0, s8, 0x2000
	s_nop 0
	global_load_lds_dwordx4 v[138:139], off
	s_waitcnt vmcnt(6)
	s_barrier
	s_setprio 1
	v_mfma_f32_16x16x32_bf16 v[60:63], v[224:227], v[192:195], v[60:63]
	v_mfma_f32_16x16x32_bf16 v[52:55], v[232:235], v[192:195], v[52:55]
	v_mfma_f32_16x16x32_bf16 v[44:47], v[224:227], v[200:203], v[44:47]
	v_mfma_f32_16x16x32_bf16 v[36:39], v[232:235], v[200:203], v[36:39]
	v_mfma_f32_16x16x32_bf16 v[28:31], v[224:227], v[208:211], v[28:31]
	v_mfma_f32_16x16x32_bf16 v[20:23], v[232:235], v[208:211], v[20:23]
	v_mfma_f32_16x16x32_bf16 v[12:15], v[224:227], v[216:219], v[12:15]
	v_mfma_f32_16x16x32_bf16 v[4:7], v[232:235], v[216:219], v[4:7]
	v_mfma_f32_16x16x32_bf16 v[60:63], v[228:231], v[196:199], v[60:63]
	v_mfma_f32_16x16x32_bf16 v[52:55], v[236:239], v[196:199], v[52:55]
	v_mfma_f32_16x16x32_bf16 v[44:47], v[228:231], v[204:207], v[44:47]
	v_mfma_f32_16x16x32_bf16 v[36:39], v[236:239], v[204:207], v[36:39]
	v_mfma_f32_16x16x32_bf16 v[28:31], v[228:231], v[212:215], v[28:31]
	v_mfma_f32_16x16x32_bf16 v[20:23], v[236:239], v[212:215], v[20:23]
	v_mfma_f32_16x16x32_bf16 v[12:15], v[228:231], v[220:223], v[12:15]
	v_mfma_f32_16x16x32_bf16 v[4:7], v[236:239], v[220:223], v[4:7]
	s_setprio 0
	s_add_u32 s10, s10, 0x100
	s_addc_u32 s11, s11, 0
	s_add_u32 s6, s6, 0x100
	s_addc_u32 s7, s7, 0
	s_cmp_ge_i32 s28, s56
	s_mov_b32 s8, s28
	s_barrier
	s_cbranch_scc0 .LBB0_1059
	s_branch .LBB0_1050

.LBB0_1132:
	s_add_i32 s28, s8, 2
	s_add_u32 s29, s6, 0x80
	s_addc_u32 s9, s7, 0
	s_add_i32 s71, 0, 0x10000
	v_add_u32_e32 v142, s71, v189
	ds_read_b128 v[134:137], v142
	ds_read_b128 v[138:141], v142 offset:1024
	ds_read_b128 v[160:163], v142 offset:2048
	ds_read_b128 v[164:167], v142 offset:3072
	s_cmp_eq_u32 s59, s8
	s_cselect_b32 s8, s40, s29
	s_cselect_b32 s9, s41, s9
	s_cselect_b32 s49, s43, s11
	s_cselect_b32 s48, s42, s10
	v_lshl_add_u64 v[142:143], s[6:7], 0, v[132:133]
	s_add_i32 m0, s52, 0xc000
	ds_read_b128 v[168:171], v191
	ds_read_b128 v[192:195], v191 offset:1024
	ds_read_b128 v[196:199], v191 offset:2048
	ds_read_b128 v[200:203], v191 offset:3072
	ds_read_b128 v[204:207], v191 offset:4096
	ds_read_b128 v[208:211], v191 offset:5120
	ds_read_b128 v[212:215], v191 offset:6144
	ds_read_b128 v[216:219], v191 offset:7168
	global_load_lds_dwordx4 v[142:143], off
	v_lshl_add_u64 v[142:143], s[6:7], 0, v[130:131]
	s_add_i32 m0, s52, 0xe000
	s_nop 0
	global_load_lds_dwordx4 v[142:143], off
	s_waitcnt lgkmcnt(8)
	s_barrier
	s_waitcnt lgkmcnt(0)
	s_setprio 1
	v_mfma_f32_16x16x32_bf16 v[124:127], v[134:137], v[168:171], v[124:127]
	v_mfma_f32_16x16x32_bf16 v[120:123], v[160:163], v[168:171], v[120:123]
	v_mfma_f32_16x16x32_bf16 v[108:111], v[134:137], v[196:199], v[108:111]
	v_mfma_f32_16x16x32_bf16 v[104:107], v[160:163], v[196:199], v[104:107]
	v_mfma_f32_16x16x32_bf16 v[92:95], v[134:137], v[204:207], v[92:95]
	v_mfma_f32_16x16x32_bf16 v[88:91], v[160:163], v[204:207], v[88:91]
	v_mfma_f32_16x16x32_bf16 v[76:79], v[134:137], v[212:215], v[76:79]
	v_mfma_f32_16x16x32_bf16 v[72:75], v[160:163], v[212:215], v[72:75]
	v_mfma_f32_16x16x32_bf16 v[124:127], v[138:141], v[192:195], v[124:127]
	v_mfma_f32_16x16x32_bf16 v[120:123], v[164:167], v[192:195], v[120:123]
	v_mfma_f32_16x16x32_bf16 v[108:111], v[138:141], v[200:203], v[108:111]
	v_mfma_f32_16x16x32_bf16 v[104:107], v[164:167], v[200:203], v[104:107]
	v_mfma_f32_16x16x32_bf16 v[92:95], v[138:141], v[208:211], v[92:95]
	v_mfma_f32_16x16x32_bf16 v[88:91], v[164:167], v[208:211], v[88:91]
	v_mfma_f32_16x16x32_bf16 v[76:79], v[138:141], v[216:219], v[76:79]
	v_mfma_f32_16x16x32_bf16 v[72:75], v[164:167], v[216:219], v[72:75]
	s_setprio 0
	s_barrier
	s_add_i32 s29, 0, 0x14000
	v_add_u32_e32 v142, s29, v189
	s_add_i32 s71, s71, s51
	ds_read_b128 v[220:223], v142
	ds_read_b128 v[224:227], v142 offset:1024
	ds_read_b128 v[228:231], v142 offset:2048
	ds_read_b128 v[232:235], v142 offset:3072
	v_lshl_add_u64 v[142:143], s[48:49], 0, v[144:145]
	s_mov_b32 m0, s71
	v_lshl_add_u64 v[236:237], s[48:49], 0, v[128:129]
	global_load_lds_dwordx4 v[142:143], off
	s_add_i32 m0, s71, 0x2000
	s_nop 0
	global_load_lds_dwordx4 v[236:237], off
	s_barrier
	s_waitcnt lgkmcnt(0)
	s_setprio 1
	v_mfma_f32_16x16x32_bf16 v[116:119], v[220:223], v[168:171], v[116:119]
	v_mfma_f32_16x16x32_bf16 v[112:115], v[228:231], v[168:171], v[112:115]
	v_mfma_f32_16x16x32_bf16 v[100:103], v[220:223], v[196:199], v[100:103]
	v_mfma_f32_16x16x32_bf16 v[96:99], v[228:231], v[196:199], v[96:99]
	v_mfma_f32_16x16x32_bf16 v[84:87], v[220:223], v[204:207], v[84:87]
	v_mfma_f32_16x16x32_bf16 v[80:83], v[228:231], v[204:207], v[80:83]
	v_mfma_f32_16x16x32_bf16 v[68:71], v[220:223], v[212:215], v[68:71]
	v_mfma_f32_16x16x32_bf16 v[64:67], v[228:231], v[212:215], v[64:67]
	v_mfma_f32_16x16x32_bf16 v[116:119], v[224:227], v[192:195], v[116:119]
	v_mfma_f32_16x16x32_bf16 v[112:115], v[232:235], v[192:195], v[112:115]
	v_mfma_f32_16x16x32_bf16 v[100:103], v[224:227], v[200:203], v[100:103]
	v_mfma_f32_16x16x32_bf16 v[96:99], v[232:235], v[200:203], v[96:99]
	v_mfma_f32_16x16x32_bf16 v[84:87], v[224:227], v[208:211], v[84:87]
	v_mfma_f32_16x16x32_bf16 v[80:83], v[232:235], v[208:211], v[80:83]
	v_mfma_f32_16x16x32_bf16 v[68:71], v[224:227], v[216:219], v[68:71]
	v_mfma_f32_16x16x32_bf16 v[64:67], v[232:235], v[216:219], v[64:67]
	s_setprio 0
	s_mov_b32 m0, s52
	v_lshl_add_u64 v[238:239], s[8:9], 0, v[144:145]
	s_barrier
	ds_read_b128 v[168:171], v191 offset:16384
	ds_read_b128 v[192:195], v191 offset:17408
	ds_read_b128 v[196:199], v191 offset:18432
	ds_read_b128 v[200:203], v191 offset:19456
	ds_read_b128 v[204:207], v191 offset:20480
	ds_read_b128 v[208:211], v191 offset:21504
	ds_read_b128 v[212:215], v191 offset:22528
	ds_read_b128 v[216:219], v191 offset:23552
	global_load_lds_dwordx4 v[238:239], off
	v_lshl_add_u64 v[240:241], s[8:9], 0, v[128:129]
	s_mov_b32 m0, s53
	s_nop 0
	global_load_lds_dwordx4 v[240:241], off
	s_barrier
	s_waitcnt lgkmcnt(0)
	s_setprio 1
	v_mfma_f32_16x16x32_bf16 v[60:63], v[134:137], v[168:171], v[60:63]
	v_mfma_f32_16x16x32_bf16 v[56:59], v[160:163], v[168:171], v[56:59]
	v_mfma_f32_16x16x32_bf16 v[44:47], v[134:137], v[196:199], v[44:47]
	v_mfma_f32_16x16x32_bf16 v[40:43], v[160:163], v[196:199], v[40:43]
	v_mfma_f32_16x16x32_bf16 v[28:31], v[134:137], v[204:207], v[28:31]
	v_mfma_f32_16x16x32_bf16 v[24:27], v[160:163], v[204:207], v[24:27]
	v_mfma_f32_16x16x32_bf16 v[12:15], v[134:137], v[212:215], v[12:15]
	v_mfma_f32_16x16x32_bf16 v[8:11], v[160:163], v[212:215], v[8:11]
	v_mfma_f32_16x16x32_bf16 v[60:63], v[138:141], v[192:195], v[60:63]
	v_mfma_f32_16x16x32_bf16 v[56:59], v[164:167], v[192:195], v[56:59]
	v_mfma_f32_16x16x32_bf16 v[44:47], v[138:141], v[200:203], v[44:47]
	v_mfma_f32_16x16x32_bf16 v[40:43], v[164:167], v[200:203], v[40:43]
	v_mfma_f32_16x16x32_bf16 v[28:31], v[138:141], v[208:211], v[28:31]
	v_mfma_f32_16x16x32_bf16 v[24:27], v[164:167], v[208:211], v[24:27]
	v_mfma_f32_16x16x32_bf16 v[12:15], v[138:141], v[216:219], v[12:15]
	v_mfma_f32_16x16x32_bf16 v[8:11], v[164:167], v[216:219], v[8:11]
	s_setprio 0
	s_barrier
	s_add_u32 s48, s48, s44
	s_addc_u32 s49, s49, s45
	s_add_i32 s29, s29, s51
	v_lshl_add_u64 v[242:243], s[48:49], 0, v[144:145]
	s_mov_b32 m0, s29
	v_lshl_add_u64 v[244:245], s[48:49], 0, v[128:129]
	global_load_lds_dwordx4 v[242:243], off
	s_add_i32 m0, s29, 0x2000
	s_nop 0
	global_load_lds_dwordx4 v[244:245], off
	s_waitcnt vmcnt(6)
	s_barrier
	s_setprio 1
	v_mfma_f32_16x16x32_bf16 v[52:55], v[220:223], v[168:171], v[52:55]
	v_mfma_f32_16x16x32_bf16 v[48:51], v[228:231], v[168:171], v[48:51]
	v_mfma_f32_16x16x32_bf16 v[36:39], v[220:223], v[196:199], v[36:39]
	v_mfma_f32_16x16x32_bf16 v[32:35], v[228:231], v[196:199], v[32:35]
	v_mfma_f32_16x16x32_bf16 v[20:23], v[220:223], v[204:207], v[20:23]
	v_mfma_f32_16x16x32_bf16 v[16:19], v[228:231], v[204:207], v[16:19]
	v_mfma_f32_16x16x32_bf16 v[4:7], v[220:223], v[212:215], v[4:7]
	v_mfma_f32_16x16x32_bf16 v[0:3], v[228:231], v[212:215], v[0:3]
	v_mfma_f32_16x16x32_bf16 v[52:55], v[224:227], v[192:195], v[52:55]
	v_mfma_f32_16x16x32_bf16 v[48:51], v[232:235], v[192:195], v[48:51]
	v_mfma_f32_16x16x32_bf16 v[36:39], v[224:227], v[200:203], v[36:39]
	v_mfma_f32_16x16x32_bf16 v[32:35], v[232:235], v[200:203], v[32:35]
	v_mfma_f32_16x16x32_bf16 v[20:23], v[224:227], v[208:211], v[20:23]
	v_mfma_f32_16x16x32_bf16 v[16:19], v[232:235], v[208:211], v[16:19]
	v_mfma_f32_16x16x32_bf16 v[4:7], v[224:227], v[216:219], v[4:7]
	v_mfma_f32_16x16x32_bf16 v[0:3], v[232:235], v[216:219], v[0:3]
	s_setprio 0
	s_add_i32 s29, 0, 0x18000
	v_add_u32_e32 v164, s29, v189
	s_barrier
	ds_read_b128 v[134:137], v164
	ds_read_b128 v[138:141], v164 offset:1024
	ds_read_b128 v[160:163], v164 offset:2048
	ds_read_b128 v[164:167], v164 offset:3072
	s_add_u32 s8, s8, s44
	s_addc_u32 s9, s9, s45
	s_mov_b32 m0, s54
	v_lshl_add_u64 v[220:221], s[8:9], 0, v[144:145]
	ds_read_b128 v[168:171], v191 offset:32768
	ds_read_b128 v[192:195], v191 offset:33792
	ds_read_b128 v[196:199], v191 offset:34816
	ds_read_b128 v[200:203], v191 offset:35840
	ds_read_b128 v[204:207], v191 offset:36864
	ds_read_b128 v[208:211], v191 offset:37888
	ds_read_b128 v[212:215], v191 offset:38912
	ds_read_b128 v[216:219], v191 offset:39936
	global_load_lds_dwordx4 v[220:221], off
	v_lshl_add_u64 v[220:221], s[8:9], 0, v[128:129]
	s_mov_b32 m0, s55
	s_nop 0
	global_load_lds_dwordx4 v[220:221], off
	s_waitcnt lgkmcnt(8)
	s_barrier
	s_waitcnt lgkmcnt(0)
	s_setprio 1
	v_mfma_f32_16x16x32_bf16 v[124:127], v[134:137], v[168:171], v[124:127]
	v_mfma_f32_16x16x32_bf16 v[120:123], v[160:163], v[168:171], v[120:123]
	v_mfma_f32_16x16x32_bf16 v[108:111], v[134:137], v[196:199], v[108:111]
	v_mfma_f32_16x16x32_bf16 v[104:107], v[160:163], v[196:199], v[104:107]
	v_mfma_f32_16x16x32_bf16 v[92:95], v[134:137], v[204:207], v[92:95]
	v_mfma_f32_16x16x32_bf16 v[88:91], v[160:163], v[204:207], v[88:91]
	v_mfma_f32_16x16x32_bf16 v[76:79], v[134:137], v[212:215], v[76:79]
	v_mfma_f32_16x16x32_bf16 v[72:75], v[160:163], v[212:215], v[72:75]
	v_mfma_f32_16x16x32_bf16 v[124:127], v[138:141], v[192:195], v[124:127]
	v_mfma_f32_16x16x32_bf16 v[120:123], v[164:167], v[192:195], v[120:123]
	v_mfma_f32_16x16x32_bf16 v[108:111], v[138:141], v[200:203], v[108:111]
	v_mfma_f32_16x16x32_bf16 v[104:107], v[164:167], v[200:203], v[104:107]
	v_mfma_f32_16x16x32_bf16 v[92:95], v[138:141], v[208:211], v[92:95]
	v_mfma_f32_16x16x32_bf16 v[88:91], v[164:167], v[208:211], v[88:91]
	v_mfma_f32_16x16x32_bf16 v[76:79], v[138:141], v[216:219], v[76:79]
	v_mfma_f32_16x16x32_bf16 v[72:75], v[164:167], v[216:219], v[72:75]
	s_setprio 0
	s_barrier
	s_add_i32 s8, 0, 0x1c000
	s_add_i32 s9, s29, s51
	v_add_u32_e32 v232, s8, v189
	v_lshl_add_u64 v[142:143], v[142:143], 0, s[82:83]
	s_mov_b32 m0, s9
	ds_read_b128 v[220:223], v232
	ds_read_b128 v[224:227], v232 offset:1024
	ds_read_b128 v[228:231], v232 offset:2048
	ds_read_b128 v[232:235], v232 offset:3072
	global_load_lds_dwordx4 v[142:143], off
	v_lshl_add_u64 v[142:143], v[236:237], 0, s[82:83]
	s_add_i32 m0, s9, 0x2000
	s_nop 0
	global_load_lds_dwordx4 v[142:143], off
	s_barrier
	s_waitcnt lgkmcnt(0)
	s_setprio 1
	v_mfma_f32_16x16x32_bf16 v[116:119], v[220:223], v[168:171], v[116:119]
	v_mfma_f32_16x16x32_bf16 v[112:115], v[228:231], v[168:171], v[112:115]
	v_mfma_f32_16x16x32_bf16 v[100:103], v[220:223], v[196:199], v[100:103]
	v_mfma_f32_16x16x32_bf16 v[96:99], v[228:231], v[196:199], v[96:99]
	v_mfma_f32_16x16x32_bf16 v[84:87], v[220:223], v[204:207], v[84:87]
	v_mfma_f32_16x16x32_bf16 v[80:83], v[228:231], v[204:207], v[80:83]
	v_mfma_f32_16x16x32_bf16 v[68:71], v[220:223], v[212:215], v[68:71]
	v_mfma_f32_16x16x32_bf16 v[64:67], v[228:231], v[212:215], v[64:67]
	v_mfma_f32_16x16x32_bf16 v[116:119], v[224:227], v[192:195], v[116:119]
	v_mfma_f32_16x16x32_bf16 v[112:115], v[232:235], v[192:195], v[112:115]
	v_mfma_f32_16x16x32_bf16 v[100:103], v[224:227], v[200:203], v[100:103]
	v_mfma_f32_16x16x32_bf16 v[96:99], v[232:235], v[200:203], v[96:99]
	v_mfma_f32_16x16x32_bf16 v[84:87], v[224:227], v[208:211], v[84:87]
	v_mfma_f32_16x16x32_bf16 v[80:83], v[232:235], v[208:211], v[80:83]
	v_mfma_f32_16x16x32_bf16 v[68:71], v[224:227], v[216:219], v[68:71]
	v_mfma_f32_16x16x32_bf16 v[64:67], v[232:235], v[216:219], v[64:67]
	s_setprio 0
	s_mov_b32 m0, s57
	v_lshl_add_u64 v[142:143], v[238:239], 0, s[82:83]
	s_barrier
	ds_read_b128 v[168:171], v191 offset:49152
	ds_read_b128 v[192:195], v191 offset:50176
	ds_read_b128 v[196:199], v191 offset:51200
	ds_read_b128 v[200:203], v191 offset:52224
	ds_read_b128 v[204:207], v191 offset:53248
	ds_read_b128 v[208:211], v191 offset:54272
	ds_read_b128 v[212:215], v191 offset:55296
	ds_read_b128 v[216:219], v191 offset:56320
	global_load_lds_dwordx4 v[142:143], off
	v_lshl_add_u64 v[142:143], v[240:241], 0, s[82:83]
	s_mov_b32 m0, s58
	s_nop 0
	global_load_lds_dwordx4 v[142:143], off
	s_barrier
	s_waitcnt lgkmcnt(0)
	s_setprio 1
	v_mfma_f32_16x16x32_bf16 v[60:63], v[134:137], v[168:171], v[60:63]
	v_mfma_f32_16x16x32_bf16 v[56:59], v[160:163], v[168:171], v[56:59]
	v_mfma_f32_16x16x32_bf16 v[44:47], v[134:137], v[196:199], v[44:47]
	v_mfma_f32_16x16x32_bf16 v[40:43], v[160:163], v[196:199], v[40:43]
	v_mfma_f32_16x16x32_bf16 v[28:31], v[134:137], v[204:207], v[28:31]
	v_mfma_f32_16x16x32_bf16 v[24:27], v[160:163], v[204:207], v[24:27]
	v_mfma_f32_16x16x32_bf16 v[12:15], v[134:137], v[212:215], v[12:15]
	v_mfma_f32_16x16x32_bf16 v[8:11], v[160:163], v[212:215], v[8:11]
	v_mfma_f32_16x16x32_bf16 v[60:63], v[138:141], v[192:195], v[60:63]
	v_mfma_f32_16x16x32_bf16 v[56:59], v[164:167], v[192:195], v[56:59]
	v_mfma_f32_16x16x32_bf16 v[44:47], v[138:141], v[200:203], v[44:47]
	v_mfma_f32_16x16x32_bf16 v[40:43], v[164:167], v[200:203], v[40:43]
	v_mfma_f32_16x16x32_bf16 v[28:31], v[138:141], v[208:211], v[28:31]
	v_mfma_f32_16x16x32_bf16 v[24:27], v[164:167], v[208:211], v[24:27]
	v_mfma_f32_16x16x32_bf16 v[12:15], v[138:141], v[216:219], v[12:15]
	v_mfma_f32_16x16x32_bf16 v[8:11], v[164:167], v[216:219], v[8:11]
	s_setprio 0
	s_barrier
	s_add_i32 s8, s8, s51
	v_lshl_add_u64 v[134:135], v[242:243], 0, s[82:83]
	s_mov_b32 m0, s8
	s_nop 0
	global_load_lds_dwordx4 v[134:135], off
	v_lshl_add_u64 v[134:135], v[244:245], 0, s[82:83]
	s_add_i32 m0, s8, 0x2000
	s_nop 0
	global_load_lds_dwordx4 v[134:135], off
	s_waitcnt vmcnt(6)
	s_barrier
	s_setprio 1
	v_mfma_f32_16x16x32_bf16 v[52:55], v[220:223], v[168:171], v[52:55]
	v_mfma_f32_16x16x32_bf16 v[48:51], v[228:231], v[168:171], v[48:51]
	v_mfma_f32_16x16x32_bf16 v[36:39], v[220:223], v[196:199], v[36:39]
	v_mfma_f32_16x16x32_bf16 v[32:35], v[228:231], v[196:199], v[32:35]
	v_mfma_f32_16x16x32_bf16 v[20:23], v[220:223], v[204:207], v[20:23]
	v_mfma_f32_16x16x32_bf16 v[16:19], v[228:231], v[204:207], v[16:19]
	v_mfma_f32_16x16x32_bf16 v[4:7], v[220:223], v[212:215], v[4:7]
	v_mfma_f32_16x16x32_bf16 v[0:3], v[228:231], v[212:215], v[0:3]
	v_mfma_f32_16x16x32_bf16 v[52:55], v[224:227], v[192:195], v[52:55]
	v_mfma_f32_16x16x32_bf16 v[48:51], v[232:235], v[192:195], v[48:51]
	v_mfma_f32_16x16x32_bf16 v[36:39], v[224:227], v[200:203], v[36:39]
	v_mfma_f32_16x16x32_bf16 v[32:35], v[232:235], v[200:203], v[32:35]
	v_mfma_f32_16x16x32_bf16 v[20:23], v[224:227], v[208:211], v[20:23]
	v_mfma_f32_16x16x32_bf16 v[16:19], v[232:235], v[208:211], v[16:19]
	v_mfma_f32_16x16x32_bf16 v[4:7], v[224:227], v[216:219], v[4:7]
	v_mfma_f32_16x16x32_bf16 v[0:3], v[232:235], v[216:219], v[0:3]
	s_setprio 0
	s_add_u32 s10, s10, 0x100
	s_addc_u32 s11, s11, 0
	s_add_u32 s6, s6, 0x100
	s_addc_u32 s7, s7, 0
	s_cmp_ge_i32 s28, s56
	s_mov_b32 s8, s28
	s_barrier
	s_cbranch_scc0 .LBB0_1132
	s_branch .LBB0_1119
